# RWKV scan: last output-reduction level fused into v_add_f32_dpp (15 fewer instrs per tile); restore v162:163 constant after hand-off poll
# speedup vs baseline: 1.0062x; 1.0027x over previous
.LBB0_595:
	s_andn2_saveexec_b64 s[0:1], s[20:21]
	s_cbranch_execz .LBB0_609
	s_bitcmp1_b32 s25, 0
	s_cselect_b32 s20, 0x6000, 0
	v_add_u32_e32 v1, s20, v143
	ds_read_b128 v[32:35], v1
	ds_read_b128 v[40:43], v1 offset:16
	s_and_b32 s20, s25, 1
	s_mul_i32 s21, s20, 0x6000
	s_add_i32 s21, s21, 0
	s_waitcnt lgkmcnt(1)
	v_pk_mul_f32 v[2:3], v[66:67], v[34:35] op_sel_hi:[1,0]
	v_pk_mul_f32 v[34:35], v[64:65], v[34:35] op_sel:[0,1]
	v_pk_fma_f32 v[2:3], v[70:71], v[32:33], v[2:3] op_sel_hi:[1,0,1]
	v_pk_fma_f32 v[32:33], v[68:69], v[32:33], v[34:35] op_sel:[0,1,0]
	s_waitcnt lgkmcnt(0)
	v_pk_fma_f32 v[2:3], v[62:63], v[40:41], v[2:3] op_sel_hi:[1,0,1]
	v_pk_fma_f32 v[32:33], v[60:61], v[40:41], v[32:33] op_sel:[0,1,0]
	v_pk_fma_f32 v[2:3], v[46:47], v[42:43], v[2:3] op_sel_hi:[1,0,1]
	v_pk_fma_f32 v[32:33], v[44:45], v[42:43], v[32:33] op_sel:[0,1,0]
	v_lshl_add_u32 v152, v97, 2, s21
	v_pk_add_f32 v[2:3], v[2:3], v[32:33]
	v_lshl_add_u32 v151, v98, 2, s21
	ds_read_b128 v[72:75], v152 offset:4096
	ds_read_b128 v[154:157], v152 offset:4112
	ds_read_b128 v[158:161], v152 offset:8192
	ds_read_b128 v[166:169], v152 offset:8208
	ds_read_b128 v[170:173], v152 offset:12288
	ds_read_b128 v[174:177], v152 offset:12304
	ds_read_b128 v[178:181], v152 offset:16384
	ds_read_b128 v[198:201], v152 offset:16400
	ds_read_b64 v[202:203], v151 offset:20480
	ds_read_b128 v[36:39], v1 offset:256
	ds_read_b128 v[28:31], v1 offset:272
	v_add_f32_dpp v2, v2, v2 quad_perm:[1,0,3,2] row_mask:0xf bank_mask:0xf bound_ctrl:1
	v_add_f32_dpp v3, v3, v3 quad_perm:[1,0,3,2] row_mask:0xf bank_mask:0xf bound_ctrl:1
	s_lshl_b32 s20, s20, 12
	v_add_u32_e32 v153, s20, v99
	v_add_f32_dpp v2, v2, v2 quad_perm:[2,3,0,1] row_mask:0xf bank_mask:0xf bound_ctrl:1
	v_add_f32_dpp v3, v3, v3 quad_perm:[2,3,0,1] row_mask:0xf bank_mask:0xf bound_ctrl:1
	s_nop 0
	v_add_f32_dpp v32, v2, v2 row_half_mirror row_mask:0xf bank_mask:0xf bound_ctrl:1
	v_add_f32_dpp v33, v3, v3 row_half_mirror row_mask:0xf bank_mask:0xf bound_ctrl:1
	s_waitcnt lgkmcnt(8)
	v_pk_mul_f32 v[2:3], v[158:159], v[32:33] op_sel_hi:[0,1]
	s_waitcnt lgkmcnt(2)
	v_pk_fma_f32 v[2:3], v[170:171], v[202:203], v[2:3] op_sel_hi:[0,1,1] neg_lo:[0,0,1] neg_hi:[0,0,1]
	v_pk_mul_f32 v[34:35], v[158:159], v[32:33] op_sel:[1,0]
	v_pk_fma_f32 v[2:3], v[70:71], v[72:73], v[2:3] op_sel_hi:[1,0,1]
	v_pk_fma_f32 v[34:35], v[170:171], v[202:203], v[34:35] op_sel:[1,0,0] neg_lo:[0,0,1] neg_hi:[0,0,1]
	v_pk_mul_f32 v[42:43], v[160:161], v[32:33] op_sel_hi:[0,1]
	v_pk_fma_f32 v[68:69], v[68:69], v[72:73], v[34:35] op_sel:[0,1,0]
	v_pk_fma_f32 v[42:43], v[172:173], v[202:203], v[42:43] op_sel_hi:[0,1,1] neg_lo:[0,0,1] neg_hi:[0,0,1]
	v_pk_mul_f32 v[70:71], v[160:161], v[32:33] op_sel:[1,0]
	v_pk_fma_f32 v[66:67], v[66:67], v[74:75], v[42:43] op_sel_hi:[1,0,1]
	v_pk_fma_f32 v[70:71], v[172:173], v[202:203], v[70:71] op_sel:[1,0,0] neg_lo:[0,0,1] neg_hi:[0,0,1]
	v_pk_fma_f32 v[40:41], v[178:179], v[68:69], 0 op_sel:[1,0,0] op_sel_hi:[1,1,0]
	v_pk_fma_f32 v[64:65], v[64:65], v[74:75], v[70:71] op_sel:[0,1,0]
	v_pk_fma_f32 v[40:41], v[180:181], v[64:65], v[40:41] op_sel:[1,0,0]
	v_pk_mul_f32 v[42:43], v[166:167], v[32:33] op_sel_hi:[0,1]
	v_pk_fma_f32 v[42:43], v[174:175], v[202:203], v[42:43] op_sel_hi:[0,1,1] neg_lo:[0,0,1] neg_hi:[0,0,1]
	v_pk_fma_f32 v[62:63], v[62:63], v[154:155], v[42:43] op_sel_hi:[1,0,1]
	v_pk_mul_f32 v[42:43], v[166:167], v[32:33] op_sel:[1,0]
	v_pk_fma_f32 v[34:35], v[178:179], v[2:3], 0 op_sel_hi:[0,1,0]
	v_pk_fma_f32 v[42:43], v[174:175], v[202:203], v[42:43] op_sel:[1,0,0] neg_lo:[0,0,1] neg_hi:[0,0,1]
	v_pk_fma_f32 v[60:61], v[60:61], v[154:155], v[42:43] op_sel:[0,1,0]
	v_pk_mul_f32 v[42:43], v[168:169], v[32:33] op_sel_hi:[0,1]
	v_pk_fma_f32 v[34:35], v[180:181], v[66:67], v[34:35] op_sel_hi:[0,1,1]
	v_pk_fma_f32 v[42:43], v[176:177], v[202:203], v[42:43] op_sel_hi:[0,1,1] neg_lo:[0,0,1] neg_hi:[0,0,1]
	v_pk_mul_f32 v[32:33], v[168:169], v[32:33] op_sel:[1,0]
	v_pk_fma_f32 v[34:35], v[198:199], v[62:63], v[34:35] op_sel_hi:[0,1,1]
	v_pk_fma_f32 v[46:47], v[46:47], v[156:157], v[42:43] op_sel_hi:[1,0,1]
	v_pk_fma_f32 v[32:33], v[176:177], v[202:203], v[32:33] op_sel:[1,0,0] neg_lo:[0,0,1] neg_hi:[0,0,1]
	v_pk_fma_f32 v[40:41], v[198:199], v[60:61], v[40:41] op_sel:[1,0,0]
	v_pk_fma_f32 v[44:45], v[44:45], v[156:157], v[32:33] op_sel:[0,1,0]
	v_pk_fma_f32 v[32:33], v[200:201], v[46:47], v[34:35] op_sel_hi:[0,1,1]
	v_pk_fma_f32 v[34:35], v[200:201], v[44:45], v[40:41] op_sel:[1,0,0]
	v_pk_add_f32 v[32:33], v[32:33], v[34:35]
	s_nop 1
	v_add_f32_dpp v32, v32, v32 quad_perm:[1,0,3,2] row_mask:0xf bank_mask:0xf bound_ctrl:1
	v_add_f32_dpp v33, v33, v33 quad_perm:[1,0,3,2] row_mask:0xf bank_mask:0xf bound_ctrl:1
	s_nop 0
	v_add_f32_dpp v32, v32, v32 quad_perm:[2,3,0,1] row_mask:0xf bank_mask:0xf bound_ctrl:1
	v_add_f32_dpp v33, v33, v33 quad_perm:[2,3,0,1] row_mask:0xf bank_mask:0xf bound_ctrl:1
	s_nop 0
	v_add_f32_dpp v32, v32, v32 row_half_mirror row_mask:0xf bank_mask:0xf bound_ctrl:1
	v_add_f32_dpp v33, v33, v33 row_half_mirror row_mask:0xf bank_mask:0xf bound_ctrl:1
	s_and_saveexec_b64 s[20:21], s[14:15]
	ds_write_b64 v153, v[32:33] offset:49152
	s_or_b64 exec, exec, s[20:21]
	s_waitcnt lgkmcnt(1)
	v_pk_mul_f32 v[202:203], v[38:39], v[66:67] op_sel_hi:[0,1]
	v_pk_fma_f32 v[202:203], v[36:37], v[2:3], v[202:203] op_sel_hi:[0,1,1]
	v_pk_mul_f32 v[38:39], v[38:39], v[64:65] op_sel:[1,0]
	v_pk_fma_f32 v[36:37], v[36:37], v[68:69], v[38:39] op_sel:[1,0,0]
	s_waitcnt lgkmcnt(0)
	v_pk_fma_f32 v[38:39], v[28:29], v[62:63], v[202:203] op_sel_hi:[0,1,1]
	v_pk_fma_f32 v[28:29], v[28:29], v[60:61], v[36:37] op_sel:[1,0,0]
	v_pk_fma_f32 v[36:37], v[30:31], v[46:47], v[38:39] op_sel_hi:[0,1,1]
	v_pk_fma_f32 v[28:29], v[30:31], v[44:45], v[28:29] op_sel:[1,0,0]
	v_pk_add_f32 v[28:29], v[36:37], v[28:29]
	ds_read_b128 v[70:73], v152 offset:4352
	ds_read_b128 v[154:157], v152 offset:4368
	ds_read_b128 v[158:161], v152 offset:8448
	ds_read_b128 v[166:169], v152 offset:8464
	ds_read_b128 v[170:173], v152 offset:12544
	ds_read_b128 v[174:177], v152 offset:12560
	ds_read_b128 v[178:181], v152 offset:16640
	ds_read_b128 v[198:201], v152 offset:16656
	ds_read_b64 v[74:75], v151 offset:20736
	ds_read_b128 v[40:43], v1 offset:512
	ds_read_b128 v[32:35], v1 offset:528
	v_add_f32_dpp v28, v28, v28 quad_perm:[1,0,3,2] row_mask:0xf bank_mask:0xf bound_ctrl:1
	v_add_f32_dpp v29, v29, v29 quad_perm:[1,0,3,2] row_mask:0xf bank_mask:0xf bound_ctrl:1
	s_nop 0
	v_add_f32_dpp v28, v28, v28 quad_perm:[2,3,0,1] row_mask:0xf bank_mask:0xf bound_ctrl:1
	v_add_f32_dpp v29, v29, v29 quad_perm:[2,3,0,1] row_mask:0xf bank_mask:0xf bound_ctrl:1
	s_nop 0
	v_add_f32_dpp v28, v28, v28 row_half_mirror row_mask:0xf bank_mask:0xf bound_ctrl:1
	v_add_f32_dpp v29, v29, v29 row_half_mirror row_mask:0xf bank_mask:0xf bound_ctrl:1
	s_waitcnt lgkmcnt(8)
	v_pk_mul_f32 v[30:31], v[158:159], v[28:29] op_sel_hi:[0,1]
	s_waitcnt lgkmcnt(2)
	v_pk_fma_f32 v[30:31], v[170:171], v[74:75], v[30:31] op_sel_hi:[0,1,1] neg_lo:[0,0,1] neg_hi:[0,0,1]
	v_pk_fma_f32 v[2:3], v[2:3], v[70:71], v[30:31] op_sel_hi:[1,0,1]
	v_pk_mul_f32 v[30:31], v[158:159], v[28:29] op_sel:[1,0]
	v_pk_mul_f32 v[38:39], v[160:161], v[28:29] op_sel_hi:[0,1]
	v_pk_fma_f32 v[30:31], v[170:171], v[74:75], v[30:31] op_sel:[1,0,0] neg_lo:[0,0,1] neg_hi:[0,0,1]
	v_pk_fma_f32 v[38:39], v[172:173], v[74:75], v[38:39] op_sel_hi:[0,1,1] neg_lo:[0,0,1] neg_hi:[0,0,1]
	v_pk_fma_f32 v[68:69], v[68:69], v[70:71], v[30:31] op_sel:[0,1,0]
	v_pk_fma_f32 v[66:67], v[66:67], v[72:73], v[38:39] op_sel_hi:[1,0,1]
	v_pk_mul_f32 v[70:71], v[160:161], v[28:29] op_sel:[1,0]
	v_pk_fma_f32 v[70:71], v[172:173], v[74:75], v[70:71] op_sel:[1,0,0] neg_lo:[0,0,1] neg_hi:[0,0,1]
	v_pk_fma_f32 v[36:37], v[178:179], v[68:69], 0 op_sel:[1,0,0] op_sel_hi:[1,1,0]
	v_pk_fma_f32 v[64:65], v[64:65], v[72:73], v[70:71] op_sel:[0,1,0]
	v_pk_fma_f32 v[36:37], v[180:181], v[64:65], v[36:37] op_sel:[1,0,0]
	v_pk_mul_f32 v[38:39], v[166:167], v[28:29] op_sel_hi:[0,1]
	v_pk_fma_f32 v[38:39], v[174:175], v[74:75], v[38:39] op_sel_hi:[0,1,1] neg_lo:[0,0,1] neg_hi:[0,0,1]
	v_pk_fma_f32 v[62:63], v[62:63], v[154:155], v[38:39] op_sel_hi:[1,0,1]
	v_pk_mul_f32 v[38:39], v[166:167], v[28:29] op_sel:[1,0]
	v_pk_fma_f32 v[30:31], v[178:179], v[2:3], 0 op_sel_hi:[0,1,0]
	v_pk_fma_f32 v[38:39], v[174:175], v[74:75], v[38:39] op_sel:[1,0,0] neg_lo:[0,0,1] neg_hi:[0,0,1]
	v_pk_fma_f32 v[60:61], v[60:61], v[154:155], v[38:39] op_sel:[0,1,0]
	v_pk_mul_f32 v[38:39], v[168:169], v[28:29] op_sel_hi:[0,1]
	v_pk_fma_f32 v[30:31], v[180:181], v[66:67], v[30:31] op_sel_hi:[0,1,1]
	v_pk_fma_f32 v[38:39], v[176:177], v[74:75], v[38:39] op_sel_hi:[0,1,1] neg_lo:[0,0,1] neg_hi:[0,0,1]
	v_pk_mul_f32 v[28:29], v[168:169], v[28:29] op_sel:[1,0]
	v_pk_fma_f32 v[30:31], v[198:199], v[62:63], v[30:31] op_sel_hi:[0,1,1]
	v_pk_fma_f32 v[46:47], v[46:47], v[156:157], v[38:39] op_sel_hi:[1,0,1]
	v_pk_fma_f32 v[28:29], v[176:177], v[74:75], v[28:29] op_sel:[1,0,0] neg_lo:[0,0,1] neg_hi:[0,0,1]
	v_pk_fma_f32 v[36:37], v[198:199], v[60:61], v[36:37] op_sel:[1,0,0]
	v_pk_fma_f32 v[44:45], v[44:45], v[156:157], v[28:29] op_sel:[0,1,0]
	v_pk_fma_f32 v[28:29], v[200:201], v[46:47], v[30:31] op_sel_hi:[0,1,1]
	v_pk_fma_f32 v[30:31], v[200:201], v[44:45], v[36:37] op_sel:[1,0,0]
	v_pk_add_f32 v[28:29], v[28:29], v[30:31]
	s_nop 1
	v_add_f32_dpp v28, v28, v28 quad_perm:[1,0,3,2] row_mask:0xf bank_mask:0xf bound_ctrl:1
	v_add_f32_dpp v29, v29, v29 quad_perm:[1,0,3,2] row_mask:0xf bank_mask:0xf bound_ctrl:1
	s_nop 0
	v_add_f32_dpp v28, v28, v28 quad_perm:[2,3,0,1] row_mask:0xf bank_mask:0xf bound_ctrl:1
	v_add_f32_dpp v29, v29, v29 quad_perm:[2,3,0,1] row_mask:0xf bank_mask:0xf bound_ctrl:1
	s_nop 0
	v_add_f32_dpp v28, v28, v28 row_half_mirror row_mask:0xf bank_mask:0xf bound_ctrl:1
	v_add_f32_dpp v29, v29, v29 row_half_mirror row_mask:0xf bank_mask:0xf bound_ctrl:1
	s_and_saveexec_b64 s[20:21], s[14:15]
	ds_write_b64 v153, v[28:29] offset:49408
	s_or_b64 exec, exec, s[20:21]
	s_waitcnt lgkmcnt(1)
	v_pk_mul_f32 v[202:203], v[42:43], v[66:67] op_sel_hi:[0,1]
	v_pk_fma_f32 v[202:203], v[40:41], v[2:3], v[202:203] op_sel_hi:[0,1,1]
	v_pk_mul_f32 v[42:43], v[42:43], v[64:65] op_sel:[1,0]
	v_pk_fma_f32 v[40:41], v[40:41], v[68:69], v[42:43] op_sel:[1,0,0]
	s_waitcnt lgkmcnt(0)
	v_pk_fma_f32 v[42:43], v[32:33], v[62:63], v[202:203] op_sel_hi:[0,1,1]
	v_pk_fma_f32 v[32:33], v[32:33], v[60:61], v[40:41] op_sel:[1,0,0]
	v_pk_fma_f32 v[40:41], v[34:35], v[46:47], v[42:43] op_sel_hi:[0,1,1]
	v_pk_fma_f32 v[32:33], v[34:35], v[44:45], v[32:33] op_sel:[1,0,0]
	v_pk_add_f32 v[32:33], v[40:41], v[32:33]
	ds_read_b128 v[70:73], v152 offset:4608
	ds_read_b128 v[154:157], v152 offset:4624
	ds_read_b128 v[158:161], v152 offset:8704
	ds_read_b128 v[166:169], v152 offset:8720
	ds_read_b128 v[170:173], v152 offset:12800
	ds_read_b128 v[174:177], v152 offset:12816
	ds_read_b128 v[178:181], v152 offset:16896
	ds_read_b128 v[198:201], v152 offset:16912
	ds_read_b64 v[74:75], v151 offset:20992
	ds_read_b128 v[36:39], v1 offset:768
	ds_read_b128 v[28:31], v1 offset:784
	v_add_f32_dpp v32, v32, v32 quad_perm:[1,0,3,2] row_mask:0xf bank_mask:0xf bound_ctrl:1
	v_add_f32_dpp v33, v33, v33 quad_perm:[1,0,3,2] row_mask:0xf bank_mask:0xf bound_ctrl:1
	s_nop 0
	v_add_f32_dpp v32, v32, v32 quad_perm:[2,3,0,1] row_mask:0xf bank_mask:0xf bound_ctrl:1
	v_add_f32_dpp v33, v33, v33 quad_perm:[2,3,0,1] row_mask:0xf bank_mask:0xf bound_ctrl:1
	s_nop 0
	v_add_f32_dpp v32, v32, v32 row_half_mirror row_mask:0xf bank_mask:0xf bound_ctrl:1
	v_add_f32_dpp v33, v33, v33 row_half_mirror row_mask:0xf bank_mask:0xf bound_ctrl:1
	s_waitcnt lgkmcnt(8)
	v_pk_mul_f32 v[34:35], v[158:159], v[32:33] op_sel_hi:[0,1]
	s_waitcnt lgkmcnt(2)
	v_pk_fma_f32 v[34:35], v[170:171], v[74:75], v[34:35] op_sel_hi:[0,1,1] neg_lo:[0,0,1] neg_hi:[0,0,1]
	v_pk_fma_f32 v[2:3], v[2:3], v[70:71], v[34:35] op_sel_hi:[1,0,1]
	v_pk_mul_f32 v[34:35], v[158:159], v[32:33] op_sel:[1,0]
	v_pk_mul_f32 v[42:43], v[160:161], v[32:33] op_sel_hi:[0,1]
	v_pk_fma_f32 v[34:35], v[170:171], v[74:75], v[34:35] op_sel:[1,0,0] neg_lo:[0,0,1] neg_hi:[0,0,1]
	v_pk_fma_f32 v[42:43], v[172:173], v[74:75], v[42:43] op_sel_hi:[0,1,1] neg_lo:[0,0,1] neg_hi:[0,0,1]
	v_pk_fma_f32 v[68:69], v[68:69], v[70:71], v[34:35] op_sel:[0,1,0]
	v_pk_fma_f32 v[66:67], v[66:67], v[72:73], v[42:43] op_sel_hi:[1,0,1]
	v_pk_mul_f32 v[70:71], v[160:161], v[32:33] op_sel:[1,0]
	v_pk_fma_f32 v[70:71], v[172:173], v[74:75], v[70:71] op_sel:[1,0,0] neg_lo:[0,0,1] neg_hi:[0,0,1]
	v_pk_fma_f32 v[40:41], v[178:179], v[68:69], 0 op_sel:[1,0,0] op_sel_hi:[1,1,0]
	v_pk_fma_f32 v[64:65], v[64:65], v[72:73], v[70:71] op_sel:[0,1,0]
	v_pk_fma_f32 v[40:41], v[180:181], v[64:65], v[40:41] op_sel:[1,0,0]
	v_pk_mul_f32 v[42:43], v[166:167], v[32:33] op_sel_hi:[0,1]
	v_pk_fma_f32 v[42:43], v[174:175], v[74:75], v[42:43] op_sel_hi:[0,1,1] neg_lo:[0,0,1] neg_hi:[0,0,1]
	v_pk_fma_f32 v[62:63], v[62:63], v[154:155], v[42:43] op_sel_hi:[1,0,1]
	v_pk_mul_f32 v[42:43], v[166:167], v[32:33] op_sel:[1,0]
	v_pk_fma_f32 v[34:35], v[178:179], v[2:3], 0 op_sel_hi:[0,1,0]
	v_pk_fma_f32 v[42:43], v[174:175], v[74:75], v[42:43] op_sel:[1,0,0] neg_lo:[0,0,1] neg_hi:[0,0,1]
	v_pk_fma_f32 v[60:61], v[60:61], v[154:155], v[42:43] op_sel:[0,1,0]
	v_pk_mul_f32 v[42:43], v[168:169], v[32:33] op_sel_hi:[0,1]
	v_pk_fma_f32 v[34:35], v[180:181], v[66:67], v[34:35] op_sel_hi:[0,1,1]
	v_pk_fma_f32 v[42:43], v[176:177], v[74:75], v[42:43] op_sel_hi:[0,1,1] neg_lo:[0,0,1] neg_hi:[0,0,1]
	v_pk_mul_f32 v[32:33], v[168:169], v[32:33] op_sel:[1,0]
	v_pk_fma_f32 v[34:35], v[198:199], v[62:63], v[34:35] op_sel_hi:[0,1,1]
	v_pk_fma_f32 v[46:47], v[46:47], v[156:157], v[42:43] op_sel_hi:[1,0,1]
	v_pk_fma_f32 v[32:33], v[176:177], v[74:75], v[32:33] op_sel:[1,0,0] neg_lo:[0,0,1] neg_hi:[0,0,1]
	v_pk_fma_f32 v[40:41], v[198:199], v[60:61], v[40:41] op_sel:[1,0,0]
	v_pk_fma_f32 v[44:45], v[44:45], v[156:157], v[32:33] op_sel:[0,1,0]
	v_pk_fma_f32 v[32:33], v[200:201], v[46:47], v[34:35] op_sel_hi:[0,1,1]
	v_pk_fma_f32 v[34:35], v[200:201], v[44:45], v[40:41] op_sel:[1,0,0]
	v_pk_add_f32 v[32:33], v[32:33], v[34:35]
	s_nop 1
	v_add_f32_dpp v32, v32, v32 quad_perm:[1,0,3,2] row_mask:0xf bank_mask:0xf bound_ctrl:1
	v_add_f32_dpp v33, v33, v33 quad_perm:[1,0,3,2] row_mask:0xf bank_mask:0xf bound_ctrl:1
	s_nop 0
	v_add_f32_dpp v32, v32, v32 quad_perm:[2,3,0,1] row_mask:0xf bank_mask:0xf bound_ctrl:1
	v_add_f32_dpp v33, v33, v33 quad_perm:[2,3,0,1] row_mask:0xf bank_mask:0xf bound_ctrl:1
	s_nop 0
	v_add_f32_dpp v32, v32, v32 row_half_mirror row_mask:0xf bank_mask:0xf bound_ctrl:1
	v_add_f32_dpp v33, v33, v33 row_half_mirror row_mask:0xf bank_mask:0xf bound_ctrl:1
	s_and_saveexec_b64 s[20:21], s[14:15]
	ds_write_b64 v153, v[32:33] offset:49664
	s_or_b64 exec, exec, s[20:21]
	s_waitcnt lgkmcnt(1)
	v_pk_mul_f32 v[202:203], v[38:39], v[66:67] op_sel_hi:[0,1]
	v_pk_fma_f32 v[202:203], v[36:37], v[2:3], v[202:203] op_sel_hi:[0,1,1]
	v_pk_mul_f32 v[38:39], v[38:39], v[64:65] op_sel:[1,0]
	v_pk_fma_f32 v[36:37], v[36:37], v[68:69], v[38:39] op_sel:[1,0,0]
	s_waitcnt lgkmcnt(0)
	v_pk_fma_f32 v[38:39], v[28:29], v[62:63], v[202:203] op_sel_hi:[0,1,1]
	v_pk_fma_f32 v[28:29], v[28:29], v[60:61], v[36:37] op_sel:[1,0,0]
	v_pk_fma_f32 v[36:37], v[30:31], v[46:47], v[38:39] op_sel_hi:[0,1,1]
	v_pk_fma_f32 v[28:29], v[30:31], v[44:45], v[28:29] op_sel:[1,0,0]
	v_pk_add_f32 v[28:29], v[36:37], v[28:29]
	ds_read_b128 v[70:73], v152 offset:4864
	ds_read_b128 v[154:157], v152 offset:4880
	ds_read_b128 v[158:161], v152 offset:8960
	ds_read_b128 v[166:169], v152 offset:8976
	ds_read_b128 v[170:173], v152 offset:13056
	ds_read_b128 v[174:177], v152 offset:13072
	ds_read_b128 v[178:181], v152 offset:17152
	ds_read_b128 v[198:201], v152 offset:17168
	ds_read_b64 v[74:75], v151 offset:21248
	ds_read_b128 v[40:43], v1 offset:1024
	ds_read_b128 v[32:35], v1 offset:1040
	v_add_f32_dpp v28, v28, v28 quad_perm:[1,0,3,2] row_mask:0xf bank_mask:0xf bound_ctrl:1
	v_add_f32_dpp v29, v29, v29 quad_perm:[1,0,3,2] row_mask:0xf bank_mask:0xf bound_ctrl:1
	s_nop 0
	v_add_f32_dpp v28, v28, v28 quad_perm:[2,3,0,1] row_mask:0xf bank_mask:0xf bound_ctrl:1
	v_add_f32_dpp v29, v29, v29 quad_perm:[2,3,0,1] row_mask:0xf bank_mask:0xf bound_ctrl:1
	s_nop 0
	v_add_f32_dpp v36, v28, v28 row_half_mirror row_mask:0xf bank_mask:0xf bound_ctrl:1
	v_add_f32_dpp v37, v29, v29 row_half_mirror row_mask:0xf bank_mask:0xf bound_ctrl:1
	s_waitcnt lgkmcnt(8)
	v_pk_mul_f32 v[28:29], v[158:159], v[36:37] op_sel_hi:[0,1]
	s_waitcnt lgkmcnt(2)
	v_pk_fma_f32 v[28:29], v[170:171], v[74:75], v[28:29] op_sel_hi:[0,1,1] neg_lo:[0,0,1] neg_hi:[0,0,1]
	v_pk_fma_f32 v[2:3], v[2:3], v[70:71], v[28:29] op_sel_hi:[1,0,1]
	v_pk_mul_f32 v[28:29], v[158:159], v[36:37] op_sel:[1,0]
	v_pk_mul_f32 v[30:31], v[160:161], v[36:37] op_sel_hi:[0,1]
	v_pk_fma_f32 v[28:29], v[170:171], v[74:75], v[28:29] op_sel:[1,0,0] neg_lo:[0,0,1] neg_hi:[0,0,1]
	v_pk_fma_f32 v[30:31], v[172:173], v[74:75], v[30:31] op_sel_hi:[0,1,1] neg_lo:[0,0,1] neg_hi:[0,0,1]
	v_pk_fma_f32 v[28:29], v[68:69], v[70:71], v[28:29] op_sel:[0,1,0]
	v_pk_fma_f32 v[30:31], v[66:67], v[72:73], v[30:31] op_sel_hi:[1,0,1]
	v_pk_mul_f32 v[70:71], v[160:161], v[36:37] op_sel:[1,0]
	v_pk_fma_f32 v[70:71], v[172:173], v[74:75], v[70:71] op_sel:[1,0,0] neg_lo:[0,0,1] neg_hi:[0,0,1]
	v_pk_fma_f32 v[68:69], v[178:179], v[28:29], 0 op_sel:[1,0,0] op_sel_hi:[1,1,0]
	v_pk_fma_f32 v[64:65], v[64:65], v[72:73], v[70:71] op_sel:[0,1,0]
	v_pk_fma_f32 v[66:67], v[180:181], v[64:65], v[68:69] op_sel:[1,0,0]
	v_pk_mul_f32 v[68:69], v[166:167], v[36:37] op_sel_hi:[0,1]
	v_pk_fma_f32 v[68:69], v[174:175], v[74:75], v[68:69] op_sel_hi:[0,1,1] neg_lo:[0,0,1] neg_hi:[0,0,1]
	v_pk_fma_f32 v[62:63], v[62:63], v[154:155], v[68:69] op_sel_hi:[1,0,1]
	v_pk_mul_f32 v[68:69], v[166:167], v[36:37] op_sel:[1,0]
	v_pk_fma_f32 v[38:39], v[178:179], v[2:3], 0 op_sel_hi:[0,1,0]
	v_pk_fma_f32 v[68:69], v[174:175], v[74:75], v[68:69] op_sel:[1,0,0] neg_lo:[0,0,1] neg_hi:[0,0,1]
	v_pk_fma_f32 v[38:39], v[180:181], v[30:31], v[38:39] op_sel_hi:[0,1,1]
	v_pk_fma_f32 v[60:61], v[60:61], v[154:155], v[68:69] op_sel:[0,1,0]
	v_pk_fma_f32 v[70:71], v[198:199], v[60:61], v[66:67] op_sel:[1,0,0]
	v_pk_mul_f32 v[66:67], v[168:169], v[36:37] op_sel_hi:[0,1]
	v_pk_fma_f32 v[66:67], v[176:177], v[74:75], v[66:67] op_sel_hi:[0,1,1] neg_lo:[0,0,1] neg_hi:[0,0,1]
	v_pk_mul_f32 v[36:37], v[168:169], v[36:37] op_sel:[1,0]
	v_pk_fma_f32 v[38:39], v[198:199], v[62:63], v[38:39] op_sel_hi:[0,1,1]
	v_pk_fma_f32 v[66:67], v[46:47], v[156:157], v[66:67] op_sel_hi:[1,0,1]
	v_pk_fma_f32 v[36:37], v[176:177], v[74:75], v[36:37] op_sel:[1,0,0] neg_lo:[0,0,1] neg_hi:[0,0,1]
	v_pk_fma_f32 v[68:69], v[44:45], v[156:157], v[36:37] op_sel:[0,1,0]
	v_pk_fma_f32 v[36:37], v[200:201], v[66:67], v[38:39] op_sel_hi:[0,1,1]
	v_pk_fma_f32 v[38:39], v[200:201], v[68:69], v[70:71] op_sel:[1,0,0]
	v_pk_add_f32 v[36:37], v[36:37], v[38:39]
	s_nop 1
	v_add_f32_dpp v36, v36, v36 quad_perm:[1,0,3,2] row_mask:0xf bank_mask:0xf bound_ctrl:1
	v_add_f32_dpp v37, v37, v37 quad_perm:[1,0,3,2] row_mask:0xf bank_mask:0xf bound_ctrl:1
	s_nop 0
	v_add_f32_dpp v36, v36, v36 quad_perm:[2,3,0,1] row_mask:0xf bank_mask:0xf bound_ctrl:1
	v_add_f32_dpp v37, v37, v37 quad_perm:[2,3,0,1] row_mask:0xf bank_mask:0xf bound_ctrl:1
	s_nop 0
	v_add_f32_dpp v36, v36, v36 row_half_mirror row_mask:0xf bank_mask:0xf bound_ctrl:1
	v_add_f32_dpp v37, v37, v37 row_half_mirror row_mask:0xf bank_mask:0xf bound_ctrl:1
	s_and_saveexec_b64 s[20:21], s[14:15]
	ds_write_b64 v153, v[36:37] offset:49920
	s_or_b64 exec, exec, s[20:21]
	s_waitcnt lgkmcnt(1)
	v_pk_mul_f32 v[202:203], v[42:43], v[30:31] op_sel_hi:[0,1]
	v_pk_fma_f32 v[202:203], v[40:41], v[2:3], v[202:203] op_sel_hi:[0,1,1]
	v_pk_mul_f32 v[42:43], v[42:43], v[64:65] op_sel:[1,0]
	v_pk_fma_f32 v[40:41], v[40:41], v[28:29], v[42:43] op_sel:[1,0,0]
	s_waitcnt lgkmcnt(0)
	v_pk_fma_f32 v[42:43], v[32:33], v[62:63], v[202:203] op_sel_hi:[0,1,1]
	v_pk_fma_f32 v[32:33], v[32:33], v[60:61], v[40:41] op_sel:[1,0,0]
	v_pk_fma_f32 v[40:41], v[34:35], v[66:67], v[42:43] op_sel_hi:[0,1,1]
	v_pk_fma_f32 v[32:33], v[34:35], v[68:69], v[32:33] op_sel:[1,0,0]
	v_pk_add_f32 v[32:33], v[40:41], v[32:33]
	ds_read_b128 v[70:73], v152 offset:5120
	ds_read_b128 v[154:157], v152 offset:5136
	ds_read_b128 v[158:161], v152 offset:9216
	ds_read_b128 v[166:169], v152 offset:9232
	ds_read_b128 v[170:173], v152 offset:13312
	ds_read_b128 v[174:177], v152 offset:13328
	ds_read_b128 v[178:181], v152 offset:17408
	ds_read_b128 v[198:201], v152 offset:17424
	ds_read_b64 v[74:75], v151 offset:21504
	ds_read_b128 v[44:47], v1 offset:1280
	ds_read_b128 v[36:39], v1 offset:1296
	v_add_f32_dpp v32, v32, v32 quad_perm:[1,0,3,2] row_mask:0xf bank_mask:0xf bound_ctrl:1
	v_add_f32_dpp v33, v33, v33 quad_perm:[1,0,3,2] row_mask:0xf bank_mask:0xf bound_ctrl:1
	s_nop 0
	v_add_f32_dpp v32, v32, v32 quad_perm:[2,3,0,1] row_mask:0xf bank_mask:0xf bound_ctrl:1
	v_add_f32_dpp v33, v33, v33 quad_perm:[2,3,0,1] row_mask:0xf bank_mask:0xf bound_ctrl:1
	s_nop 0
	v_add_f32_dpp v32, v32, v32 row_half_mirror row_mask:0xf bank_mask:0xf bound_ctrl:1
	v_add_f32_dpp v33, v33, v33 row_half_mirror row_mask:0xf bank_mask:0xf bound_ctrl:1
	s_waitcnt lgkmcnt(8)
	v_pk_mul_f32 v[34:35], v[158:159], v[32:33] op_sel_hi:[0,1]
	s_waitcnt lgkmcnt(2)
	v_pk_fma_f32 v[34:35], v[170:171], v[74:75], v[34:35] op_sel_hi:[0,1,1] neg_lo:[0,0,1] neg_hi:[0,0,1]
	v_pk_fma_f32 v[2:3], v[2:3], v[70:71], v[34:35] op_sel_hi:[1,0,1]
	v_pk_mul_f32 v[34:35], v[158:159], v[32:33] op_sel:[1,0]
	v_pk_mul_f32 v[42:43], v[160:161], v[32:33] op_sel_hi:[0,1]
	v_pk_fma_f32 v[34:35], v[170:171], v[74:75], v[34:35] op_sel:[1,0,0] neg_lo:[0,0,1] neg_hi:[0,0,1]
	v_pk_fma_f32 v[42:43], v[172:173], v[74:75], v[42:43] op_sel_hi:[0,1,1] neg_lo:[0,0,1] neg_hi:[0,0,1]
	v_pk_fma_f32 v[40:41], v[28:29], v[70:71], v[34:35] op_sel:[0,1,0]
	v_pk_fma_f32 v[42:43], v[30:31], v[72:73], v[42:43] op_sel_hi:[1,0,1]
	v_pk_mul_f32 v[70:71], v[160:161], v[32:33] op_sel:[1,0]
	v_pk_fma_f32 v[70:71], v[172:173], v[74:75], v[70:71] op_sel:[1,0,0] neg_lo:[0,0,1] neg_hi:[0,0,1]
	v_pk_fma_f32 v[34:35], v[178:179], v[40:41], 0 op_sel:[1,0,0] op_sel_hi:[1,1,0]
	v_pk_fma_f32 v[64:65], v[64:65], v[72:73], v[70:71] op_sel:[0,1,0]
	v_pk_fma_f32 v[30:31], v[180:181], v[64:65], v[34:35] op_sel:[1,0,0]
	v_pk_mul_f32 v[34:35], v[166:167], v[32:33] op_sel_hi:[0,1]
	v_pk_fma_f32 v[34:35], v[174:175], v[74:75], v[34:35] op_sel_hi:[0,1,1] neg_lo:[0,0,1] neg_hi:[0,0,1]
	v_pk_fma_f32 v[62:63], v[62:63], v[154:155], v[34:35] op_sel_hi:[1,0,1]
	v_pk_mul_f32 v[34:35], v[166:167], v[32:33] op_sel:[1,0]
	v_pk_fma_f32 v[28:29], v[178:179], v[2:3], 0 op_sel_hi:[0,1,0]
	v_pk_fma_f32 v[34:35], v[174:175], v[74:75], v[34:35] op_sel:[1,0,0] neg_lo:[0,0,1] neg_hi:[0,0,1]
	v_pk_fma_f32 v[60:61], v[60:61], v[154:155], v[34:35] op_sel:[0,1,0]
	v_pk_mul_f32 v[34:35], v[168:169], v[32:33] op_sel_hi:[0,1]
	v_pk_fma_f32 v[34:35], v[176:177], v[74:75], v[34:35] op_sel_hi:[0,1,1] neg_lo:[0,0,1] neg_hi:[0,0,1]
	v_pk_fma_f32 v[72:73], v[66:67], v[156:157], v[34:35] op_sel_hi:[1,0,1]
	v_pk_mul_f32 v[32:33], v[168:169], v[32:33] op_sel:[1,0]
	v_pk_fma_f32 v[28:29], v[180:181], v[42:43], v[28:29] op_sel_hi:[0,1,1]
	v_pk_fma_f32 v[32:33], v[176:177], v[74:75], v[32:33] op_sel:[1,0,0] neg_lo:[0,0,1] neg_hi:[0,0,1]
	v_pk_fma_f32 v[28:29], v[198:199], v[62:63], v[28:29] op_sel_hi:[0,1,1]
	v_pk_fma_f32 v[30:31], v[198:199], v[60:61], v[30:31] op_sel:[1,0,0]
	v_pk_fma_f32 v[74:75], v[68:69], v[156:157], v[32:33] op_sel:[0,1,0]
	v_pk_fma_f32 v[28:29], v[200:201], v[72:73], v[28:29] op_sel_hi:[0,1,1]
	v_pk_fma_f32 v[30:31], v[200:201], v[74:75], v[30:31] op_sel:[1,0,0]
	v_pk_add_f32 v[28:29], v[28:29], v[30:31]
	s_nop 1
	v_add_f32_dpp v28, v28, v28 quad_perm:[1,0,3,2] row_mask:0xf bank_mask:0xf bound_ctrl:1
	v_add_f32_dpp v29, v29, v29 quad_perm:[1,0,3,2] row_mask:0xf bank_mask:0xf bound_ctrl:1
	s_nop 0
	v_add_f32_dpp v28, v28, v28 quad_perm:[2,3,0,1] row_mask:0xf bank_mask:0xf bound_ctrl:1
	v_add_f32_dpp v29, v29, v29 quad_perm:[2,3,0,1] row_mask:0xf bank_mask:0xf bound_ctrl:1
	s_nop 0
	v_add_f32_dpp v28, v28, v28 row_half_mirror row_mask:0xf bank_mask:0xf bound_ctrl:1
	v_add_f32_dpp v29, v29, v29 row_half_mirror row_mask:0xf bank_mask:0xf bound_ctrl:1
	s_and_saveexec_b64 s[20:21], s[14:15]
	ds_write_b64 v153, v[28:29] offset:50176
	s_or_b64 exec, exec, s[20:21]
	s_waitcnt lgkmcnt(1)
	v_pk_mul_f32 v[66:67], v[46:47], v[42:43] op_sel_hi:[0,1]
	v_pk_fma_f32 v[66:67], v[44:45], v[2:3], v[66:67] op_sel_hi:[0,1,1]
	v_pk_mul_f32 v[46:47], v[46:47], v[64:65] op_sel:[1,0]
	v_pk_fma_f32 v[44:45], v[44:45], v[40:41], v[46:47] op_sel:[1,0,0]
	s_waitcnt lgkmcnt(0)
	v_pk_fma_f32 v[46:47], v[36:37], v[62:63], v[66:67] op_sel_hi:[0,1,1]
	v_pk_fma_f32 v[36:37], v[36:37], v[60:61], v[44:45] op_sel:[1,0,0]
	v_pk_fma_f32 v[44:45], v[38:39], v[72:73], v[46:47] op_sel_hi:[0,1,1]
	v_pk_fma_f32 v[36:37], v[38:39], v[74:75], v[36:37] op_sel:[1,0,0]
	v_pk_add_f32 v[36:37], v[44:45], v[36:37]
	ds_read_b128 v[154:157], v152 offset:5376
	ds_read_b128 v[158:161], v152 offset:5392
	ds_read_b128 v[166:169], v152 offset:9472
	ds_read_b128 v[170:173], v152 offset:9488
	ds_read_b128 v[174:177], v152 offset:13568
	ds_read_b128 v[178:181], v152 offset:13584
	ds_read_b128 v[198:201], v152 offset:17664
	ds_read_b128 v[202:205], v152 offset:17680
	ds_read_b64 v[206:207], v151 offset:21760
	ds_read_b128 v[32:35], v1 offset:1536
	ds_read_b128 v[28:31], v1 offset:1552
	v_add_f32_dpp v36, v36, v36 quad_perm:[1,0,3,2] row_mask:0xf bank_mask:0xf bound_ctrl:1
	v_add_f32_dpp v37, v37, v37 quad_perm:[1,0,3,2] row_mask:0xf bank_mask:0xf bound_ctrl:1
	s_nop 0
	s_waitcnt lgkmcnt(6)
	v_add_f32_dpp v36, v36, v36 quad_perm:[2,3,0,1] row_mask:0xf bank_mask:0xf bound_ctrl:1
	v_add_f32_dpp v37, v37, v37 quad_perm:[2,3,0,1] row_mask:0xf bank_mask:0xf bound_ctrl:1
	s_nop 0
	v_add_f32_dpp v36, v36, v36 row_half_mirror row_mask:0xf bank_mask:0xf bound_ctrl:1
	v_add_f32_dpp v37, v37, v37 row_half_mirror row_mask:0xf bank_mask:0xf bound_ctrl:1
	s_nop 0
	v_pk_mul_f32 v[38:39], v[166:167], v[36:37] op_sel_hi:[0,1]
	s_waitcnt lgkmcnt(2)
	v_pk_fma_f32 v[38:39], v[174:175], v[206:207], v[38:39] op_sel_hi:[0,1,1] neg_lo:[0,0,1] neg_hi:[0,0,1]
	v_pk_fma_f32 v[70:71], v[2:3], v[154:155], v[38:39] op_sel_hi:[1,0,1]
	v_pk_mul_f32 v[2:3], v[166:167], v[36:37] op_sel:[1,0]
	s_nop 0
	v_pk_fma_f32 v[2:3], v[174:175], v[206:207], v[2:3] op_sel:[1,0,0] neg_lo:[0,0,1] neg_hi:[0,0,1]
	s_nop 0
	v_pk_fma_f32 v[68:69], v[40:41], v[154:155], v[2:3] op_sel:[0,1,0]
	v_pk_mul_f32 v[40:41], v[168:169], v[36:37] op_sel_hi:[0,1]
	v_pk_fma_f32 v[40:41], v[176:177], v[206:207], v[40:41] op_sel_hi:[0,1,1] neg_lo:[0,0,1] neg_hi:[0,0,1]
	v_pk_fma_f32 v[66:67], v[42:43], v[156:157], v[40:41] op_sel_hi:[1,0,1]
	v_pk_mul_f32 v[42:43], v[168:169], v[36:37] op_sel:[1,0]
	v_pk_fma_f32 v[42:43], v[176:177], v[206:207], v[42:43] op_sel:[1,0,0] neg_lo:[0,0,1] neg_hi:[0,0,1]
	v_pk_fma_f32 v[38:39], v[198:199], v[68:69], 0 op_sel:[1,0,0] op_sel_hi:[1,1,0]
	v_pk_fma_f32 v[64:65], v[64:65], v[156:157], v[42:43] op_sel:[0,1,0]
	v_pk_fma_f32 v[38:39], v[200:201], v[64:65], v[38:39] op_sel:[1,0,0]
	v_pk_mul_f32 v[40:41], v[170:171], v[36:37] op_sel_hi:[0,1]
	v_pk_fma_f32 v[40:41], v[178:179], v[206:207], v[40:41] op_sel_hi:[0,1,1] neg_lo:[0,0,1] neg_hi:[0,0,1]
	v_pk_fma_f32 v[62:63], v[62:63], v[158:159], v[40:41] op_sel_hi:[1,0,1]
	v_pk_mul_f32 v[40:41], v[170:171], v[36:37] op_sel:[1,0]
	v_mov_b32_e32 v42, v173
	v_pk_fma_f32 v[40:41], v[178:179], v[206:207], v[40:41] op_sel:[1,0,0] neg_lo:[0,0,1] neg_hi:[0,0,1]
	v_pk_fma_f32 v[2:3], v[198:199], v[70:71], 0 op_sel_hi:[0,1,0]
	v_pk_fma_f32 v[60:61], v[60:61], v[158:159], v[40:41] op_sel:[0,1,0]
	v_pk_mul_f32 v[40:41], v[172:173], v[36:37] op_sel_hi:[0,1]
	v_pk_fma_f32 v[40:41], v[180:181], v[206:207], v[40:41] op_sel_hi:[0,1,1] neg_lo:[0,0,1] neg_hi:[0,0,1]
	v_pk_mul_f32 v[36:37], v[42:43], v[36:37] op_sel_hi:[0,1]
	v_pk_fma_f32 v[2:3], v[200:201], v[66:67], v[2:3] op_sel_hi:[0,1,1]
	v_pk_fma_f32 v[46:47], v[72:73], v[160:161], v[40:41] op_sel_hi:[1,0,1]
	v_mov_b32_e32 v40, v161
	v_pk_fma_f32 v[36:37], v[180:181], v[206:207], v[36:37] op_sel:[1,0,0] neg_lo:[0,0,1] neg_hi:[0,0,1]
	v_pk_fma_f32 v[2:3], v[202:203], v[62:63], v[2:3] op_sel_hi:[0,1,1]
	v_pk_fma_f32 v[38:39], v[202:203], v[60:61], v[38:39] op_sel:[1,0,0]
	v_pk_fma_f32 v[44:45], v[74:75], v[40:41], v[36:37] op_sel_hi:[1,0,1]
	v_pk_fma_f32 v[2:3], v[204:205], v[46:47], v[2:3] op_sel_hi:[0,1,1]
	v_pk_fma_f32 v[36:37], v[204:205], v[44:45], v[38:39] op_sel:[1,0,0]
	v_pk_add_f32 v[2:3], v[2:3], v[36:37]
	s_nop 1
	v_add_f32_dpp v2, v2, v2 quad_perm:[1,0,3,2] row_mask:0xf bank_mask:0xf bound_ctrl:1
	v_add_f32_dpp v3, v3, v3 quad_perm:[1,0,3,2] row_mask:0xf bank_mask:0xf bound_ctrl:1
	s_nop 0
	v_add_f32_dpp v2, v2, v2 quad_perm:[2,3,0,1] row_mask:0xf bank_mask:0xf bound_ctrl:1
	v_add_f32_dpp v3, v3, v3 quad_perm:[2,3,0,1] row_mask:0xf bank_mask:0xf bound_ctrl:1
	s_nop 0
	v_add_f32_dpp v2, v2, v2 row_half_mirror row_mask:0xf bank_mask:0xf bound_ctrl:1
	v_add_f32_dpp v3, v3, v3 row_half_mirror row_mask:0xf bank_mask:0xf bound_ctrl:1
	s_and_saveexec_b64 s[20:21], s[14:15]
	ds_write_b64 v153, v[2:3] offset:50432
	s_or_b64 exec, exec, s[20:21]

.LBB0_612:
	s_andn2_saveexec_b64 s[0:1], s[0:1]
	s_cbranch_execz .LBB0_624
	v_pk_mul_f32 v[2:3], v[66:67], v[34:35] op_sel_hi:[1,0]
	v_pk_fma_f32 v[2:3], v[70:71], v[32:33], v[2:3] op_sel_hi:[1,0,1]
	v_pk_mul_f32 v[34:35], v[64:65], v[34:35] op_sel:[0,1]
	v_pk_fma_f32 v[2:3], v[62:63], v[28:29], v[2:3] op_sel_hi:[1,0,1]
	v_pk_fma_f32 v[32:33], v[68:69], v[32:33], v[34:35] op_sel:[0,1,0]
	v_pk_fma_f32 v[2:3], v[46:47], v[30:31], v[2:3] op_sel_hi:[1,0,1]
	v_pk_fma_f32 v[28:29], v[60:61], v[28:29], v[32:33] op_sel:[0,1,0]
	v_pk_fma_f32 v[28:29], v[44:45], v[30:31], v[28:29] op_sel:[0,1,0]
	s_and_b32 s20, s25, 1
	v_pk_add_f32 v[2:3], v[2:3], v[28:29]
	s_mul_i32 s21, s20, 0x6000
	s_add_i32 s21, s21, 0
	v_add_f32_dpp v2, v2, v2 quad_perm:[1,0,3,2] row_mask:0xf bank_mask:0xf bound_ctrl:1
	v_add_f32_dpp v3, v3, v3 quad_perm:[1,0,3,2] row_mask:0xf bank_mask:0xf bound_ctrl:1
	s_bitcmp1_b32 s25, 0
	v_lshl_add_u32 v152, v97, 2, s21
	v_mov_b32_dpp v28, v2 quad_perm:[2,3,0,1] row_mask:0xf bank_mask:0xf bound_ctrl:1
	v_mov_b32_dpp v29, v3 quad_perm:[2,3,0,1] row_mask:0xf bank_mask:0xf bound_ctrl:1
	v_lshl_add_u32 v1, v98, 2, s21
	s_cselect_b32 s21, 0x6000, 0
	v_pk_add_f32 v[2:3], v[2:3], v[28:29]
	v_add_u32_e32 v151, s21, v143
	ds_read_b128 v[72:75], v152 offset:5632
	ds_read_b128 v[154:157], v152 offset:5648
	ds_read_b128 v[158:161], v152 offset:9728
	ds_read_b128 v[166:169], v152 offset:9744
	ds_read_b128 v[170:173], v152 offset:13824
	ds_read_b128 v[174:177], v152 offset:13840
	ds_read_b128 v[178:181], v152 offset:17920
	ds_read_b128 v[198:201], v152 offset:17936
	ds_read_b64 v[202:203], v1 offset:22016
	ds_read_b128 v[40:43], v151 offset:1792
	ds_read_b128 v[36:39], v151 offset:1808
	v_add_f32_dpp v28, v2, v2 row_half_mirror row_mask:0xf bank_mask:0xf bound_ctrl:1
	v_add_f32_dpp v29, v3, v3 row_half_mirror row_mask:0xf bank_mask:0xf bound_ctrl:1
	s_lshl_b32 s20, s20, 12
	s_waitcnt lgkmcnt(8)
	v_pk_mul_f32 v[2:3], v[158:159], v[28:29] op_sel_hi:[0,1]
	s_waitcnt lgkmcnt(2)
	v_pk_fma_f32 v[2:3], v[170:171], v[202:203], v[2:3] op_sel_hi:[0,1,1] neg_lo:[0,0,1] neg_hi:[0,0,1]
	v_pk_mul_f32 v[30:31], v[158:159], v[28:29] op_sel:[1,0]
	v_pk_fma_f32 v[2:3], v[70:71], v[72:73], v[2:3] op_sel_hi:[1,0,1]
	v_pk_fma_f32 v[30:31], v[170:171], v[202:203], v[30:31] op_sel:[1,0,0] neg_lo:[0,0,1] neg_hi:[0,0,1]
	v_pk_mul_f32 v[34:35], v[160:161], v[28:29] op_sel_hi:[0,1]
	v_pk_fma_f32 v[32:33], v[68:69], v[72:73], v[30:31] op_sel:[0,1,0]
	v_pk_fma_f32 v[34:35], v[172:173], v[202:203], v[34:35] op_sel_hi:[0,1,1] neg_lo:[0,0,1] neg_hi:[0,0,1]
	v_pk_mul_f32 v[70:71], v[160:161], v[28:29] op_sel:[1,0]
	v_pk_fma_f32 v[34:35], v[66:67], v[74:75], v[34:35] op_sel_hi:[1,0,1]
	v_pk_fma_f32 v[70:71], v[172:173], v[202:203], v[70:71] op_sel:[1,0,0] neg_lo:[0,0,1] neg_hi:[0,0,1]
	v_pk_fma_f32 v[68:69], v[178:179], v[32:33], 0 op_sel:[1,0,0] op_sel_hi:[1,1,0]
	v_pk_fma_f32 v[64:65], v[64:65], v[74:75], v[70:71] op_sel:[0,1,0]
	v_pk_fma_f32 v[66:67], v[180:181], v[64:65], v[68:69] op_sel:[1,0,0]
	v_pk_mul_f32 v[68:69], v[166:167], v[28:29] op_sel_hi:[0,1]
	v_pk_fma_f32 v[68:69], v[174:175], v[202:203], v[68:69] op_sel_hi:[0,1,1] neg_lo:[0,0,1] neg_hi:[0,0,1]
	v_pk_fma_f32 v[62:63], v[62:63], v[154:155], v[68:69] op_sel_hi:[1,0,1]
	v_pk_mul_f32 v[68:69], v[166:167], v[28:29] op_sel:[1,0]
	v_pk_fma_f32 v[30:31], v[178:179], v[2:3], 0 op_sel_hi:[0,1,0]
	v_pk_fma_f32 v[68:69], v[174:175], v[202:203], v[68:69] op_sel:[1,0,0] neg_lo:[0,0,1] neg_hi:[0,0,1]
	v_pk_fma_f32 v[30:31], v[180:181], v[34:35], v[30:31] op_sel_hi:[0,1,1]
	v_pk_fma_f32 v[60:61], v[60:61], v[154:155], v[68:69] op_sel:[0,1,0]
	v_pk_fma_f32 v[70:71], v[198:199], v[60:61], v[66:67] op_sel:[1,0,0]
	v_pk_mul_f32 v[66:67], v[168:169], v[28:29] op_sel_hi:[0,1]
	v_pk_fma_f32 v[66:67], v[176:177], v[202:203], v[66:67] op_sel_hi:[0,1,1] neg_lo:[0,0,1] neg_hi:[0,0,1]
	v_pk_mul_f32 v[28:29], v[168:169], v[28:29] op_sel:[1,0]
	v_pk_fma_f32 v[30:31], v[198:199], v[62:63], v[30:31] op_sel_hi:[0,1,1]
	v_pk_fma_f32 v[66:67], v[46:47], v[156:157], v[66:67] op_sel_hi:[1,0,1]
	v_pk_fma_f32 v[28:29], v[176:177], v[202:203], v[28:29] op_sel:[1,0,0] neg_lo:[0,0,1] neg_hi:[0,0,1]
	v_pk_fma_f32 v[68:69], v[44:45], v[156:157], v[28:29] op_sel:[0,1,0]
	v_pk_fma_f32 v[28:29], v[200:201], v[66:67], v[30:31] op_sel_hi:[0,1,1]
	v_pk_fma_f32 v[30:31], v[200:201], v[68:69], v[70:71] op_sel:[1,0,0]
	v_pk_add_f32 v[28:29], v[28:29], v[30:31]
	v_add_u32_e32 v153, s20, v99
	s_nop 0
	v_add_f32_dpp v28, v28, v28 quad_perm:[1,0,3,2] row_mask:0xf bank_mask:0xf bound_ctrl:1
	v_add_f32_dpp v29, v29, v29 quad_perm:[1,0,3,2] row_mask:0xf bank_mask:0xf bound_ctrl:1
	s_nop 0
	v_add_f32_dpp v28, v28, v28 quad_perm:[2,3,0,1] row_mask:0xf bank_mask:0xf bound_ctrl:1
	v_add_f32_dpp v29, v29, v29 quad_perm:[2,3,0,1] row_mask:0xf bank_mask:0xf bound_ctrl:1
	s_nop 0
	v_add_f32_dpp v28, v28, v28 row_half_mirror row_mask:0xf bank_mask:0xf bound_ctrl:1
	v_add_f32_dpp v29, v29, v29 row_half_mirror row_mask:0xf bank_mask:0xf bound_ctrl:1
	s_and_saveexec_b64 s[20:21], s[14:15]
	ds_write_b64 v153, v[28:29] offset:50688
	s_or_b64 exec, exec, s[20:21]
	s_waitcnt lgkmcnt(1)
	v_pk_mul_f32 v[202:203], v[42:43], v[34:35] op_sel_hi:[0,1]
	v_pk_fma_f32 v[202:203], v[40:41], v[2:3], v[202:203] op_sel_hi:[0,1,1]
	v_pk_mul_f32 v[42:43], v[42:43], v[64:65] op_sel:[1,0]
	v_pk_fma_f32 v[40:41], v[40:41], v[32:33], v[42:43] op_sel:[1,0,0]
	s_waitcnt lgkmcnt(0)
	v_pk_fma_f32 v[42:43], v[36:37], v[62:63], v[202:203] op_sel_hi:[0,1,1]
	v_pk_fma_f32 v[36:37], v[36:37], v[60:61], v[40:41] op_sel:[1,0,0]
	v_pk_fma_f32 v[40:41], v[38:39], v[66:67], v[42:43] op_sel_hi:[0,1,1]
	v_pk_fma_f32 v[36:37], v[38:39], v[68:69], v[36:37] op_sel:[1,0,0]
	v_pk_add_f32 v[36:37], v[40:41], v[36:37]
	ds_read_b128 v[70:73], v152 offset:5888
	ds_read_b128 v[154:157], v152 offset:5904
	ds_read_b128 v[158:161], v152 offset:9984
	ds_read_b128 v[166:169], v152 offset:10000
	ds_read_b128 v[170:173], v152 offset:14080
	ds_read_b128 v[174:177], v152 offset:14096
	ds_read_b128 v[178:181], v152 offset:18176
	ds_read_b128 v[198:201], v152 offset:18192
	ds_read_b64 v[74:75], v1 offset:22272
	ds_read_b128 v[44:47], v151 offset:2048
	ds_read_b128 v[28:31], v151 offset:2064
	v_add_f32_dpp v36, v36, v36 quad_perm:[1,0,3,2] row_mask:0xf bank_mask:0xf bound_ctrl:1
	v_add_f32_dpp v37, v37, v37 quad_perm:[1,0,3,2] row_mask:0xf bank_mask:0xf bound_ctrl:1
	s_nop 0
	v_add_f32_dpp v36, v36, v36 quad_perm:[2,3,0,1] row_mask:0xf bank_mask:0xf bound_ctrl:1
	v_add_f32_dpp v37, v37, v37 quad_perm:[2,3,0,1] row_mask:0xf bank_mask:0xf bound_ctrl:1
	s_nop 0
	v_add_f32_dpp v40, v36, v36 row_half_mirror row_mask:0xf bank_mask:0xf bound_ctrl:1
	v_add_f32_dpp v41, v37, v37 row_half_mirror row_mask:0xf bank_mask:0xf bound_ctrl:1
	s_waitcnt lgkmcnt(8)
	v_pk_mul_f32 v[36:37], v[158:159], v[40:41] op_sel_hi:[0,1]
	s_waitcnt lgkmcnt(2)
	v_pk_fma_f32 v[36:37], v[170:171], v[74:75], v[36:37] op_sel_hi:[0,1,1] neg_lo:[0,0,1] neg_hi:[0,0,1]
	v_pk_fma_f32 v[2:3], v[2:3], v[70:71], v[36:37] op_sel_hi:[1,0,1]
	v_pk_mul_f32 v[36:37], v[158:159], v[40:41] op_sel:[1,0]
	v_pk_mul_f32 v[38:39], v[160:161], v[40:41] op_sel_hi:[0,1]
	v_pk_fma_f32 v[36:37], v[170:171], v[74:75], v[36:37] op_sel:[1,0,0] neg_lo:[0,0,1] neg_hi:[0,0,1]
	v_pk_fma_f32 v[38:39], v[172:173], v[74:75], v[38:39] op_sel_hi:[0,1,1] neg_lo:[0,0,1] neg_hi:[0,0,1]
	v_pk_fma_f32 v[36:37], v[32:33], v[70:71], v[36:37] op_sel:[0,1,0]
	v_pk_fma_f32 v[38:39], v[34:35], v[72:73], v[38:39] op_sel_hi:[1,0,1]
	v_pk_mul_f32 v[70:71], v[160:161], v[40:41] op_sel:[1,0]
	v_pk_fma_f32 v[70:71], v[172:173], v[74:75], v[70:71] op_sel:[1,0,0] neg_lo:[0,0,1] neg_hi:[0,0,1]
	v_pk_fma_f32 v[42:43], v[178:179], v[36:37], 0 op_sel:[1,0,0] op_sel_hi:[1,1,0]
	v_pk_fma_f32 v[64:65], v[64:65], v[72:73], v[70:71] op_sel:[0,1,0]
	v_pk_fma_f32 v[34:35], v[180:181], v[64:65], v[42:43] op_sel:[1,0,0]
	v_pk_mul_f32 v[42:43], v[166:167], v[40:41] op_sel_hi:[0,1]
	v_pk_fma_f32 v[42:43], v[174:175], v[74:75], v[42:43] op_sel_hi:[0,1,1] neg_lo:[0,0,1] neg_hi:[0,0,1]
	v_pk_fma_f32 v[62:63], v[62:63], v[154:155], v[42:43] op_sel_hi:[1,0,1]
	v_pk_mul_f32 v[42:43], v[166:167], v[40:41] op_sel:[1,0]
	v_pk_fma_f32 v[42:43], v[174:175], v[74:75], v[42:43] op_sel:[1,0,0] neg_lo:[0,0,1] neg_hi:[0,0,1]
	v_pk_fma_f32 v[32:33], v[178:179], v[2:3], 0 op_sel_hi:[0,1,0]
	v_pk_fma_f32 v[60:61], v[60:61], v[154:155], v[42:43] op_sel:[0,1,0]
	v_pk_mul_f32 v[42:43], v[168:169], v[40:41] op_sel_hi:[0,1]
	v_pk_fma_f32 v[42:43], v[176:177], v[74:75], v[42:43] op_sel_hi:[0,1,1] neg_lo:[0,0,1] neg_hi:[0,0,1]
	v_pk_mul_f32 v[40:41], v[168:169], v[40:41] op_sel:[1,0]
	v_pk_fma_f32 v[32:33], v[180:181], v[38:39], v[32:33] op_sel_hi:[0,1,1]
	v_pk_fma_f32 v[66:67], v[66:67], v[156:157], v[42:43] op_sel_hi:[1,0,1]
	v_pk_fma_f32 v[40:41], v[176:177], v[74:75], v[40:41] op_sel:[1,0,0] neg_lo:[0,0,1] neg_hi:[0,0,1]
	v_pk_fma_f32 v[32:33], v[198:199], v[62:63], v[32:33] op_sel_hi:[0,1,1]
	v_pk_fma_f32 v[34:35], v[198:199], v[60:61], v[34:35] op_sel:[1,0,0]
	v_pk_fma_f32 v[68:69], v[68:69], v[156:157], v[40:41] op_sel:[0,1,0]
	v_pk_fma_f32 v[32:33], v[200:201], v[66:67], v[32:33] op_sel_hi:[0,1,1]
	v_pk_fma_f32 v[34:35], v[200:201], v[68:69], v[34:35] op_sel:[1,0,0]
	v_pk_add_f32 v[32:33], v[32:33], v[34:35]
	s_nop 1
	v_add_f32_dpp v32, v32, v32 quad_perm:[1,0,3,2] row_mask:0xf bank_mask:0xf bound_ctrl:1
	v_add_f32_dpp v33, v33, v33 quad_perm:[1,0,3,2] row_mask:0xf bank_mask:0xf bound_ctrl:1
	s_nop 0
	v_add_f32_dpp v32, v32, v32 quad_perm:[2,3,0,1] row_mask:0xf bank_mask:0xf bound_ctrl:1
	v_add_f32_dpp v33, v33, v33 quad_perm:[2,3,0,1] row_mask:0xf bank_mask:0xf bound_ctrl:1
	s_nop 0
	v_add_f32_dpp v32, v32, v32 row_half_mirror row_mask:0xf bank_mask:0xf bound_ctrl:1
	v_add_f32_dpp v33, v33, v33 row_half_mirror row_mask:0xf bank_mask:0xf bound_ctrl:1
	s_and_saveexec_b64 s[20:21], s[14:15]
	ds_write_b64 v153, v[32:33] offset:50944
	s_or_b64 exec, exec, s[20:21]
	s_waitcnt lgkmcnt(1)
	v_pk_mul_f32 v[202:203], v[46:47], v[38:39] op_sel_hi:[0,1]
	v_pk_fma_f32 v[202:203], v[44:45], v[2:3], v[202:203] op_sel_hi:[0,1,1]
	v_pk_mul_f32 v[46:47], v[46:47], v[64:65] op_sel:[1,0]
	v_pk_fma_f32 v[44:45], v[44:45], v[36:37], v[46:47] op_sel:[1,0,0]
	s_waitcnt lgkmcnt(0)
	v_pk_fma_f32 v[46:47], v[28:29], v[62:63], v[202:203] op_sel_hi:[0,1,1]
	v_pk_fma_f32 v[28:29], v[28:29], v[60:61], v[44:45] op_sel:[1,0,0]
	v_pk_fma_f32 v[44:45], v[30:31], v[66:67], v[46:47] op_sel_hi:[0,1,1]
	v_pk_fma_f32 v[28:29], v[30:31], v[68:69], v[28:29] op_sel:[1,0,0]
	v_pk_add_f32 v[28:29], v[44:45], v[28:29]
	ds_read_b128 v[70:73], v152 offset:6144
	ds_read_b128 v[154:157], v152 offset:6160
	ds_read_b128 v[158:161], v152 offset:10240
	ds_read_b128 v[166:169], v152 offset:10256
	ds_read_b128 v[170:173], v152 offset:14336
	ds_read_b128 v[174:177], v152 offset:14352
	ds_read_b128 v[178:181], v152 offset:18432
	ds_read_b128 v[198:201], v152 offset:18448
	ds_read_b64 v[74:75], v1 offset:22528
	ds_read_b128 v[40:43], v151 offset:2304
	ds_read_b128 v[32:35], v151 offset:2320
	v_add_f32_dpp v28, v28, v28 quad_perm:[1,0,3,2] row_mask:0xf bank_mask:0xf bound_ctrl:1
	v_add_f32_dpp v29, v29, v29 quad_perm:[1,0,3,2] row_mask:0xf bank_mask:0xf bound_ctrl:1
	s_nop 0
	v_add_f32_dpp v28, v28, v28 quad_perm:[2,3,0,1] row_mask:0xf bank_mask:0xf bound_ctrl:1
	v_add_f32_dpp v29, v29, v29 quad_perm:[2,3,0,1] row_mask:0xf bank_mask:0xf bound_ctrl:1
	s_nop 0
	v_add_f32_dpp v44, v28, v28 row_half_mirror row_mask:0xf bank_mask:0xf bound_ctrl:1
	v_add_f32_dpp v45, v29, v29 row_half_mirror row_mask:0xf bank_mask:0xf bound_ctrl:1
	s_waitcnt lgkmcnt(8)
	v_pk_mul_f32 v[28:29], v[158:159], v[44:45] op_sel_hi:[0,1]
	s_waitcnt lgkmcnt(2)
	v_pk_fma_f32 v[28:29], v[170:171], v[74:75], v[28:29] op_sel_hi:[0,1,1] neg_lo:[0,0,1] neg_hi:[0,0,1]
	v_pk_fma_f32 v[2:3], v[2:3], v[70:71], v[28:29] op_sel_hi:[1,0,1]
	v_pk_mul_f32 v[28:29], v[158:159], v[44:45] op_sel:[1,0]
	v_pk_mul_f32 v[30:31], v[160:161], v[44:45] op_sel_hi:[0,1]
	v_pk_fma_f32 v[28:29], v[170:171], v[74:75], v[28:29] op_sel:[1,0,0] neg_lo:[0,0,1] neg_hi:[0,0,1]
	v_pk_fma_f32 v[30:31], v[172:173], v[74:75], v[30:31] op_sel_hi:[0,1,1] neg_lo:[0,0,1] neg_hi:[0,0,1]
	v_pk_fma_f32 v[28:29], v[36:37], v[70:71], v[28:29] op_sel:[0,1,0]
	v_pk_fma_f32 v[30:31], v[38:39], v[72:73], v[30:31] op_sel_hi:[1,0,1]
	v_pk_mul_f32 v[70:71], v[160:161], v[44:45] op_sel:[1,0]
	v_pk_fma_f32 v[70:71], v[172:173], v[74:75], v[70:71] op_sel:[1,0,0] neg_lo:[0,0,1] neg_hi:[0,0,1]
	v_pk_fma_f32 v[46:47], v[178:179], v[28:29], 0 op_sel:[1,0,0] op_sel_hi:[1,1,0]
	v_pk_fma_f32 v[64:65], v[64:65], v[72:73], v[70:71] op_sel:[0,1,0]
	v_pk_fma_f32 v[38:39], v[180:181], v[64:65], v[46:47] op_sel:[1,0,0]
	v_pk_mul_f32 v[46:47], v[166:167], v[44:45] op_sel_hi:[0,1]
	v_pk_fma_f32 v[46:47], v[174:175], v[74:75], v[46:47] op_sel_hi:[0,1,1] neg_lo:[0,0,1] neg_hi:[0,0,1]
	v_pk_fma_f32 v[62:63], v[62:63], v[154:155], v[46:47] op_sel_hi:[1,0,1]
	v_pk_mul_f32 v[46:47], v[166:167], v[44:45] op_sel:[1,0]
	v_pk_fma_f32 v[46:47], v[174:175], v[74:75], v[46:47] op_sel:[1,0,0] neg_lo:[0,0,1] neg_hi:[0,0,1]
	v_pk_fma_f32 v[36:37], v[178:179], v[2:3], 0 op_sel_hi:[0,1,0]
	v_pk_fma_f32 v[60:61], v[60:61], v[154:155], v[46:47] op_sel:[0,1,0]
	v_pk_mul_f32 v[46:47], v[168:169], v[44:45] op_sel_hi:[0,1]
	v_pk_fma_f32 v[46:47], v[176:177], v[74:75], v[46:47] op_sel_hi:[0,1,1] neg_lo:[0,0,1] neg_hi:[0,0,1]
	v_pk_mul_f32 v[44:45], v[168:169], v[44:45] op_sel:[1,0]
	v_pk_fma_f32 v[36:37], v[180:181], v[30:31], v[36:37] op_sel_hi:[0,1,1]
	v_pk_fma_f32 v[66:67], v[66:67], v[156:157], v[46:47] op_sel_hi:[1,0,1]
	v_pk_fma_f32 v[44:45], v[176:177], v[74:75], v[44:45] op_sel:[1,0,0] neg_lo:[0,0,1] neg_hi:[0,0,1]
	v_pk_fma_f32 v[36:37], v[198:199], v[62:63], v[36:37] op_sel_hi:[0,1,1]
	v_pk_fma_f32 v[38:39], v[198:199], v[60:61], v[38:39] op_sel:[1,0,0]
	v_pk_fma_f32 v[68:69], v[68:69], v[156:157], v[44:45] op_sel:[0,1,0]
	v_pk_fma_f32 v[36:37], v[200:201], v[66:67], v[36:37] op_sel_hi:[0,1,1]
	v_pk_fma_f32 v[38:39], v[200:201], v[68:69], v[38:39] op_sel:[1,0,0]
	v_pk_add_f32 v[36:37], v[36:37], v[38:39]
	s_nop 1
	v_add_f32_dpp v36, v36, v36 quad_perm:[1,0,3,2] row_mask:0xf bank_mask:0xf bound_ctrl:1
	v_add_f32_dpp v37, v37, v37 quad_perm:[1,0,3,2] row_mask:0xf bank_mask:0xf bound_ctrl:1
	s_nop 0
	v_add_f32_dpp v36, v36, v36 quad_perm:[2,3,0,1] row_mask:0xf bank_mask:0xf bound_ctrl:1
	v_add_f32_dpp v37, v37, v37 quad_perm:[2,3,0,1] row_mask:0xf bank_mask:0xf bound_ctrl:1
	s_nop 0
	v_add_f32_dpp v36, v36, v36 row_half_mirror row_mask:0xf bank_mask:0xf bound_ctrl:1
	v_add_f32_dpp v37, v37, v37 row_half_mirror row_mask:0xf bank_mask:0xf bound_ctrl:1
	s_and_saveexec_b64 s[20:21], s[14:15]
	ds_write_b64 v153, v[36:37] offset:51200
	s_or_b64 exec, exec, s[20:21]
	s_waitcnt lgkmcnt(1)
	v_pk_mul_f32 v[202:203], v[42:43], v[30:31] op_sel_hi:[0,1]
	v_pk_fma_f32 v[202:203], v[40:41], v[2:3], v[202:203] op_sel_hi:[0,1,1]
	v_pk_mul_f32 v[42:43], v[42:43], v[64:65] op_sel:[1,0]
	v_pk_fma_f32 v[40:41], v[40:41], v[28:29], v[42:43] op_sel:[1,0,0]
	s_waitcnt lgkmcnt(0)
	v_pk_fma_f32 v[42:43], v[32:33], v[62:63], v[202:203] op_sel_hi:[0,1,1]
	v_pk_fma_f32 v[32:33], v[32:33], v[60:61], v[40:41] op_sel:[1,0,0]
	v_pk_fma_f32 v[40:41], v[34:35], v[66:67], v[42:43] op_sel_hi:[0,1,1]
	v_pk_fma_f32 v[32:33], v[34:35], v[68:69], v[32:33] op_sel:[1,0,0]
	v_pk_add_f32 v[32:33], v[40:41], v[32:33]
	ds_read_b128 v[70:73], v152 offset:6400
	ds_read_b128 v[154:157], v152 offset:6416
	ds_read_b128 v[158:161], v152 offset:10496
	ds_read_b128 v[166:169], v152 offset:10512
	ds_read_b128 v[170:173], v152 offset:14592
	ds_read_b128 v[174:177], v152 offset:14608
	ds_read_b128 v[178:181], v152 offset:18688
	ds_read_b128 v[198:201], v152 offset:18704
	ds_read_b64 v[74:75], v1 offset:22784
	ds_read_b128 v[44:47], v151 offset:2560
	ds_read_b128 v[36:39], v151 offset:2576
	v_add_f32_dpp v32, v32, v32 quad_perm:[1,0,3,2] row_mask:0xf bank_mask:0xf bound_ctrl:1
	v_add_f32_dpp v33, v33, v33 quad_perm:[1,0,3,2] row_mask:0xf bank_mask:0xf bound_ctrl:1
	s_nop 0
	v_add_f32_dpp v32, v32, v32 quad_perm:[2,3,0,1] row_mask:0xf bank_mask:0xf bound_ctrl:1
	v_add_f32_dpp v33, v33, v33 quad_perm:[2,3,0,1] row_mask:0xf bank_mask:0xf bound_ctrl:1
	s_nop 0
	v_add_f32_dpp v32, v32, v32 row_half_mirror row_mask:0xf bank_mask:0xf bound_ctrl:1
	v_add_f32_dpp v33, v33, v33 row_half_mirror row_mask:0xf bank_mask:0xf bound_ctrl:1
	s_waitcnt lgkmcnt(8)
	v_pk_mul_f32 v[34:35], v[158:159], v[32:33] op_sel_hi:[0,1]
	s_waitcnt lgkmcnt(2)
	v_pk_fma_f32 v[34:35], v[170:171], v[74:75], v[34:35] op_sel_hi:[0,1,1] neg_lo:[0,0,1] neg_hi:[0,0,1]
	v_pk_fma_f32 v[2:3], v[2:3], v[70:71], v[34:35] op_sel_hi:[1,0,1]
	v_pk_mul_f32 v[34:35], v[158:159], v[32:33] op_sel:[1,0]
	v_pk_mul_f32 v[42:43], v[160:161], v[32:33] op_sel_hi:[0,1]
	v_pk_fma_f32 v[34:35], v[170:171], v[74:75], v[34:35] op_sel:[1,0,0] neg_lo:[0,0,1] neg_hi:[0,0,1]
	v_pk_fma_f32 v[42:43], v[172:173], v[74:75], v[42:43] op_sel_hi:[0,1,1] neg_lo:[0,0,1] neg_hi:[0,0,1]
	v_pk_fma_f32 v[40:41], v[28:29], v[70:71], v[34:35] op_sel:[0,1,0]
	v_pk_fma_f32 v[42:43], v[30:31], v[72:73], v[42:43] op_sel_hi:[1,0,1]
	v_pk_mul_f32 v[70:71], v[160:161], v[32:33] op_sel:[1,0]
	v_pk_fma_f32 v[70:71], v[172:173], v[74:75], v[70:71] op_sel:[1,0,0] neg_lo:[0,0,1] neg_hi:[0,0,1]
	v_pk_fma_f32 v[34:35], v[178:179], v[40:41], 0 op_sel:[1,0,0] op_sel_hi:[1,1,0]
	v_pk_fma_f32 v[64:65], v[64:65], v[72:73], v[70:71] op_sel:[0,1,0]
	v_pk_fma_f32 v[30:31], v[180:181], v[64:65], v[34:35] op_sel:[1,0,0]
	v_pk_mul_f32 v[34:35], v[166:167], v[32:33] op_sel_hi:[0,1]
	v_pk_fma_f32 v[34:35], v[174:175], v[74:75], v[34:35] op_sel_hi:[0,1,1] neg_lo:[0,0,1] neg_hi:[0,0,1]
	v_pk_fma_f32 v[62:63], v[62:63], v[154:155], v[34:35] op_sel_hi:[1,0,1]
	v_pk_mul_f32 v[34:35], v[166:167], v[32:33] op_sel:[1,0]
	v_pk_fma_f32 v[28:29], v[178:179], v[2:3], 0 op_sel_hi:[0,1,0]
	v_pk_fma_f32 v[34:35], v[174:175], v[74:75], v[34:35] op_sel:[1,0,0] neg_lo:[0,0,1] neg_hi:[0,0,1]
	v_pk_fma_f32 v[60:61], v[60:61], v[154:155], v[34:35] op_sel:[0,1,0]
	v_pk_mul_f32 v[34:35], v[168:169], v[32:33] op_sel_hi:[0,1]
	v_pk_fma_f32 v[34:35], v[176:177], v[74:75], v[34:35] op_sel_hi:[0,1,1] neg_lo:[0,0,1] neg_hi:[0,0,1]
	v_pk_fma_f32 v[72:73], v[66:67], v[156:157], v[34:35] op_sel_hi:[1,0,1]
	v_pk_mul_f32 v[32:33], v[168:169], v[32:33] op_sel:[1,0]
	v_pk_fma_f32 v[28:29], v[180:181], v[42:43], v[28:29] op_sel_hi:[0,1,1]
	v_pk_fma_f32 v[32:33], v[176:177], v[74:75], v[32:33] op_sel:[1,0,0] neg_lo:[0,0,1] neg_hi:[0,0,1]
	v_pk_fma_f32 v[28:29], v[198:199], v[62:63], v[28:29] op_sel_hi:[0,1,1]
	v_pk_fma_f32 v[30:31], v[198:199], v[60:61], v[30:31] op_sel:[1,0,0]
	v_pk_fma_f32 v[74:75], v[68:69], v[156:157], v[32:33] op_sel:[0,1,0]
	v_pk_fma_f32 v[28:29], v[200:201], v[72:73], v[28:29] op_sel_hi:[0,1,1]
	v_pk_fma_f32 v[30:31], v[200:201], v[74:75], v[30:31] op_sel:[1,0,0]
	v_pk_add_f32 v[28:29], v[28:29], v[30:31]
	s_nop 1
	v_add_f32_dpp v28, v28, v28 quad_perm:[1,0,3,2] row_mask:0xf bank_mask:0xf bound_ctrl:1
	v_add_f32_dpp v29, v29, v29 quad_perm:[1,0,3,2] row_mask:0xf bank_mask:0xf bound_ctrl:1
	s_nop 0
	v_add_f32_dpp v28, v28, v28 quad_perm:[2,3,0,1] row_mask:0xf bank_mask:0xf bound_ctrl:1
	v_add_f32_dpp v29, v29, v29 quad_perm:[2,3,0,1] row_mask:0xf bank_mask:0xf bound_ctrl:1
	s_nop 0
	v_add_f32_dpp v28, v28, v28 row_half_mirror row_mask:0xf bank_mask:0xf bound_ctrl:1
	v_add_f32_dpp v29, v29, v29 row_half_mirror row_mask:0xf bank_mask:0xf bound_ctrl:1
	s_and_saveexec_b64 s[20:21], s[14:15]
	ds_write_b64 v153, v[28:29] offset:51456
	s_or_b64 exec, exec, s[20:21]
	s_waitcnt lgkmcnt(1)
	v_pk_mul_f32 v[66:67], v[46:47], v[42:43] op_sel_hi:[0,1]
	v_pk_fma_f32 v[66:67], v[44:45], v[2:3], v[66:67] op_sel_hi:[0,1,1]
	v_pk_mul_f32 v[46:47], v[46:47], v[64:65] op_sel:[1,0]
	v_pk_fma_f32 v[44:45], v[44:45], v[40:41], v[46:47] op_sel:[1,0,0]
	s_waitcnt lgkmcnt(0)
	v_pk_fma_f32 v[46:47], v[36:37], v[62:63], v[66:67] op_sel_hi:[0,1,1]
	v_pk_fma_f32 v[36:37], v[36:37], v[60:61], v[44:45] op_sel:[1,0,0]
	v_pk_fma_f32 v[44:45], v[38:39], v[72:73], v[46:47] op_sel_hi:[0,1,1]
	v_pk_fma_f32 v[36:37], v[38:39], v[74:75], v[36:37] op_sel:[1,0,0]
	v_pk_add_f32 v[36:37], v[44:45], v[36:37]
	ds_read_b128 v[154:157], v152 offset:6656
	ds_read_b128 v[158:161], v152 offset:6672
	ds_read_b128 v[166:169], v152 offset:10752
	ds_read_b128 v[170:173], v152 offset:10768
	ds_read_b128 v[174:177], v152 offset:14848
	ds_read_b128 v[178:181], v152 offset:14864
	ds_read_b128 v[198:201], v152 offset:18944
	ds_read_b128 v[202:205], v152 offset:18960
	ds_read_b64 v[206:207], v1 offset:23040
	ds_read_b128 v[32:35], v151 offset:2816
	ds_read_b128 v[28:31], v151 offset:2832
	v_add_f32_dpp v36, v36, v36 quad_perm:[1,0,3,2] row_mask:0xf bank_mask:0xf bound_ctrl:1
	v_add_f32_dpp v37, v37, v37 quad_perm:[1,0,3,2] row_mask:0xf bank_mask:0xf bound_ctrl:1
	s_nop 0
	s_waitcnt lgkmcnt(6)
	v_add_f32_dpp v36, v36, v36 quad_perm:[2,3,0,1] row_mask:0xf bank_mask:0xf bound_ctrl:1
	v_add_f32_dpp v37, v37, v37 quad_perm:[2,3,0,1] row_mask:0xf bank_mask:0xf bound_ctrl:1
	s_nop 0
	v_add_f32_dpp v36, v36, v36 row_half_mirror row_mask:0xf bank_mask:0xf bound_ctrl:1
	v_add_f32_dpp v37, v37, v37 row_half_mirror row_mask:0xf bank_mask:0xf bound_ctrl:1
	s_nop 0
	v_pk_mul_f32 v[38:39], v[166:167], v[36:37] op_sel_hi:[0,1]
	s_waitcnt lgkmcnt(2)
	v_pk_fma_f32 v[38:39], v[174:175], v[206:207], v[38:39] op_sel_hi:[0,1,1] neg_lo:[0,0,1] neg_hi:[0,0,1]
	v_pk_fma_f32 v[70:71], v[2:3], v[154:155], v[38:39] op_sel_hi:[1,0,1]
	v_pk_mul_f32 v[2:3], v[166:167], v[36:37] op_sel:[1,0]
	s_nop 0
	v_pk_fma_f32 v[2:3], v[174:175], v[206:207], v[2:3] op_sel:[1,0,0] neg_lo:[0,0,1] neg_hi:[0,0,1]
	s_nop 0
	v_pk_fma_f32 v[68:69], v[40:41], v[154:155], v[2:3] op_sel:[0,1,0]
	v_pk_mul_f32 v[40:41], v[168:169], v[36:37] op_sel_hi:[0,1]
	v_pk_fma_f32 v[40:41], v[176:177], v[206:207], v[40:41] op_sel_hi:[0,1,1] neg_lo:[0,0,1] neg_hi:[0,0,1]
	v_pk_fma_f32 v[66:67], v[42:43], v[156:157], v[40:41] op_sel_hi:[1,0,1]
	v_pk_mul_f32 v[42:43], v[168:169], v[36:37] op_sel:[1,0]
	v_pk_fma_f32 v[42:43], v[176:177], v[206:207], v[42:43] op_sel:[1,0,0] neg_lo:[0,0,1] neg_hi:[0,0,1]
	v_pk_fma_f32 v[38:39], v[198:199], v[68:69], 0 op_sel:[1,0,0] op_sel_hi:[1,1,0]
	v_pk_fma_f32 v[64:65], v[64:65], v[156:157], v[42:43] op_sel:[0,1,0]
	v_pk_fma_f32 v[38:39], v[200:201], v[64:65], v[38:39] op_sel:[1,0,0]
	v_pk_mul_f32 v[40:41], v[170:171], v[36:37] op_sel_hi:[0,1]
	v_pk_fma_f32 v[40:41], v[178:179], v[206:207], v[40:41] op_sel_hi:[0,1,1] neg_lo:[0,0,1] neg_hi:[0,0,1]
	v_pk_fma_f32 v[62:63], v[62:63], v[158:159], v[40:41] op_sel_hi:[1,0,1]
	v_pk_mul_f32 v[40:41], v[170:171], v[36:37] op_sel:[1,0]
	v_mov_b32_e32 v42, v173
	v_pk_fma_f32 v[40:41], v[178:179], v[206:207], v[40:41] op_sel:[1,0,0] neg_lo:[0,0,1] neg_hi:[0,0,1]
	v_pk_fma_f32 v[2:3], v[198:199], v[70:71], 0 op_sel_hi:[0,1,0]
	v_pk_fma_f32 v[60:61], v[60:61], v[158:159], v[40:41] op_sel:[0,1,0]
	v_pk_mul_f32 v[40:41], v[172:173], v[36:37] op_sel_hi:[0,1]
	v_pk_fma_f32 v[40:41], v[180:181], v[206:207], v[40:41] op_sel_hi:[0,1,1] neg_lo:[0,0,1] neg_hi:[0,0,1]
	v_pk_mul_f32 v[36:37], v[42:43], v[36:37] op_sel_hi:[0,1]
	v_pk_fma_f32 v[2:3], v[200:201], v[66:67], v[2:3] op_sel_hi:[0,1,1]
	v_pk_fma_f32 v[46:47], v[72:73], v[160:161], v[40:41] op_sel_hi:[1,0,1]
	v_mov_b32_e32 v40, v161
	v_pk_fma_f32 v[36:37], v[180:181], v[206:207], v[36:37] op_sel:[1,0,0] neg_lo:[0,0,1] neg_hi:[0,0,1]
	v_pk_fma_f32 v[2:3], v[202:203], v[62:63], v[2:3] op_sel_hi:[0,1,1]
	v_pk_fma_f32 v[38:39], v[202:203], v[60:61], v[38:39] op_sel:[1,0,0]
	v_pk_fma_f32 v[44:45], v[74:75], v[40:41], v[36:37] op_sel_hi:[1,0,1]
	v_pk_fma_f32 v[2:3], v[204:205], v[46:47], v[2:3] op_sel_hi:[0,1,1]
	v_pk_fma_f32 v[36:37], v[204:205], v[44:45], v[38:39] op_sel:[1,0,0]
	v_pk_add_f32 v[2:3], v[2:3], v[36:37]
	s_nop 1
	v_add_f32_dpp v2, v2, v2 quad_perm:[1,0,3,2] row_mask:0xf bank_mask:0xf bound_ctrl:1
	v_add_f32_dpp v3, v3, v3 quad_perm:[1,0,3,2] row_mask:0xf bank_mask:0xf bound_ctrl:1
	s_nop 0
	v_add_f32_dpp v2, v2, v2 quad_perm:[2,3,0,1] row_mask:0xf bank_mask:0xf bound_ctrl:1
	v_add_f32_dpp v3, v3, v3 quad_perm:[2,3,0,1] row_mask:0xf bank_mask:0xf bound_ctrl:1
	s_nop 0
	v_add_f32_dpp v2, v2, v2 row_half_mirror row_mask:0xf bank_mask:0xf bound_ctrl:1
	v_add_f32_dpp v3, v3, v3 row_half_mirror row_mask:0xf bank_mask:0xf bound_ctrl:1
	s_and_saveexec_b64 s[20:21], s[14:15]
	ds_write_b64 v153, v[2:3] offset:51712
	s_or_b64 exec, exec, s[20:21]

.LBB0_635:
	s_andn2_saveexec_b64 s[0:1], s[0:1]
	s_cbranch_execz .LBB0_576
	v_pk_mul_f32 v[2:3], v[66:67], v[34:35] op_sel_hi:[1,0]
	v_pk_fma_f32 v[2:3], v[70:71], v[32:33], v[2:3] op_sel_hi:[1,0,1]
	v_pk_mul_f32 v[34:35], v[64:65], v[34:35] op_sel:[0,1]
	v_pk_fma_f32 v[2:3], v[62:63], v[28:29], v[2:3] op_sel_hi:[1,0,1]
	v_pk_fma_f32 v[32:33], v[68:69], v[32:33], v[34:35] op_sel:[0,1,0]
	v_pk_fma_f32 v[2:3], v[46:47], v[30:31], v[2:3] op_sel_hi:[1,0,1]
	v_pk_fma_f32 v[28:29], v[60:61], v[28:29], v[32:33] op_sel:[0,1,0]
	v_pk_fma_f32 v[28:29], v[44:45], v[30:31], v[28:29] op_sel:[0,1,0]
	s_and_b32 s20, s25, 1
	v_pk_add_f32 v[2:3], v[2:3], v[28:29]
	s_mul_i32 s21, s20, 0x6000
	s_add_i32 s21, s21, 0
	v_add_f32_dpp v2, v2, v2 quad_perm:[1,0,3,2] row_mask:0xf bank_mask:0xf bound_ctrl:1
	v_add_f32_dpp v3, v3, v3 quad_perm:[1,0,3,2] row_mask:0xf bank_mask:0xf bound_ctrl:1
	s_lshl_b32 s22, s20, 12
	s_nop 0
	s_cmp_eq_u32 s20, 1
	v_lshl_add_u32 v1, v97, 2, s21
	v_add_f32_dpp v2, v2, v2 quad_perm:[2,3,0,1] row_mask:0xf bank_mask:0xf bound_ctrl:1
	v_add_f32_dpp v3, v3, v3 quad_perm:[2,3,0,1] row_mask:0xf bank_mask:0xf bound_ctrl:1
	s_cselect_b32 s20, 0x6000, 0
	s_nop 0
	v_lshl_add_u32 v73, v98, 2, s21
	v_add_u32_e32 v74, s20, v143
	ds_read_b128 v[152:155], v1 offset:6912
	ds_read_b128 v[156:159], v1 offset:6928
	ds_read_b128 v[166:169], v1 offset:11008
	ds_read_b128 v[170:173], v1 offset:11024
	ds_read_b128 v[174:177], v1 offset:15104
	ds_read_b128 v[178:181], v1 offset:15120
	ds_read_b128 v[198:201], v1 offset:19200
	ds_read_b128 v[202:205], v1 offset:19216
	ds_read_b64 v[160:161], v73 offset:23296
	ds_read_b128 v[40:43], v74 offset:3072
	ds_read_b128 v[36:39], v74 offset:3088
	v_add_f32_dpp v28, v2, v2 row_half_mirror row_mask:0xf bank_mask:0xf bound_ctrl:1
	v_add_f32_dpp v29, v3, v3 row_half_mirror row_mask:0xf bank_mask:0xf bound_ctrl:1
	s_waitcnt lgkmcnt(6)
	v_pk_mul_f32 v[2:3], v[166:167], v[28:29] op_sel_hi:[0,1]
	s_waitcnt lgkmcnt(2)
	v_pk_fma_f32 v[2:3], v[174:175], v[160:161], v[2:3] op_sel_hi:[0,1,1] neg_lo:[0,0,1] neg_hi:[0,0,1]
	v_pk_fma_f32 v[2:3], v[70:71], v[152:153], v[2:3] op_sel_hi:[1,0,1]
	v_pk_mul_f32 v[30:31], v[166:167], v[28:29] op_sel:[1,0]
	v_pk_mul_f32 v[34:35], v[168:169], v[28:29] op_sel_hi:[0,1]
	v_pk_fma_f32 v[30:31], v[174:175], v[160:161], v[30:31] op_sel:[1,0,0] neg_lo:[0,0,1] neg_hi:[0,0,1]
	v_pk_fma_f32 v[34:35], v[176:177], v[160:161], v[34:35] op_sel_hi:[0,1,1] neg_lo:[0,0,1] neg_hi:[0,0,1]
	v_pk_mul_f32 v[70:71], v[168:169], v[28:29] op_sel:[1,0]
	v_pk_fma_f32 v[68:69], v[68:69], v[152:153], v[30:31] op_sel:[0,1,0]
	v_pk_fma_f32 v[66:67], v[66:67], v[154:155], v[34:35] op_sel_hi:[1,0,1]
	v_pk_fma_f32 v[70:71], v[176:177], v[160:161], v[70:71] op_sel:[1,0,0] neg_lo:[0,0,1] neg_hi:[0,0,1]
	v_pk_fma_f32 v[32:33], v[198:199], v[68:69], 0 op_sel:[1,0,0] op_sel_hi:[1,1,0]
	v_pk_fma_f32 v[64:65], v[64:65], v[154:155], v[70:71] op_sel:[0,1,0]
	v_pk_fma_f32 v[32:33], v[200:201], v[64:65], v[32:33] op_sel:[1,0,0]
	v_pk_mul_f32 v[34:35], v[170:171], v[28:29] op_sel_hi:[0,1]
	v_pk_fma_f32 v[34:35], v[178:179], v[160:161], v[34:35] op_sel_hi:[0,1,1] neg_lo:[0,0,1] neg_hi:[0,0,1]
	v_pk_fma_f32 v[62:63], v[62:63], v[156:157], v[34:35] op_sel_hi:[1,0,1]
	v_pk_mul_f32 v[34:35], v[170:171], v[28:29] op_sel:[1,0]
	v_pk_fma_f32 v[30:31], v[198:199], v[2:3], 0 op_sel_hi:[0,1,0]
	v_pk_fma_f32 v[34:35], v[178:179], v[160:161], v[34:35] op_sel:[1,0,0] neg_lo:[0,0,1] neg_hi:[0,0,1]
	v_pk_fma_f32 v[60:61], v[60:61], v[156:157], v[34:35] op_sel:[0,1,0]
	v_pk_mul_f32 v[34:35], v[172:173], v[28:29] op_sel_hi:[0,1]
	v_pk_fma_f32 v[30:31], v[200:201], v[66:67], v[30:31] op_sel_hi:[0,1,1]
	v_pk_fma_f32 v[34:35], v[180:181], v[160:161], v[34:35] op_sel_hi:[0,1,1] neg_lo:[0,0,1] neg_hi:[0,0,1]
	v_pk_mul_f32 v[28:29], v[172:173], v[28:29] op_sel:[1,0]
	v_pk_fma_f32 v[30:31], v[202:203], v[62:63], v[30:31] op_sel_hi:[0,1,1]
	v_pk_fma_f32 v[46:47], v[46:47], v[158:159], v[34:35] op_sel_hi:[1,0,1]
	v_pk_fma_f32 v[28:29], v[180:181], v[160:161], v[28:29] op_sel:[1,0,0] neg_lo:[0,0,1] neg_hi:[0,0,1]
	v_pk_fma_f32 v[32:33], v[202:203], v[60:61], v[32:33] op_sel:[1,0,0]
	v_pk_fma_f32 v[44:45], v[44:45], v[158:159], v[28:29] op_sel:[0,1,0]
	v_pk_fma_f32 v[28:29], v[204:205], v[46:47], v[30:31] op_sel_hi:[0,1,1]
	v_pk_fma_f32 v[30:31], v[204:205], v[44:45], v[32:33] op_sel:[1,0,0]
	v_pk_add_f32 v[28:29], v[28:29], v[30:31]
	v_add_u32_e32 v72, s22, v99
	s_nop 0
	v_add_f32_dpp v28, v28, v28 quad_perm:[1,0,3,2] row_mask:0xf bank_mask:0xf bound_ctrl:1
	v_add_f32_dpp v29, v29, v29 quad_perm:[1,0,3,2] row_mask:0xf bank_mask:0xf bound_ctrl:1
	s_nop 0
	v_add_f32_dpp v28, v28, v28 quad_perm:[2,3,0,1] row_mask:0xf bank_mask:0xf bound_ctrl:1
	v_add_f32_dpp v29, v29, v29 quad_perm:[2,3,0,1] row_mask:0xf bank_mask:0xf bound_ctrl:1
	s_nop 0
	v_add_f32_dpp v28, v28, v28 row_half_mirror row_mask:0xf bank_mask:0xf bound_ctrl:1
	v_add_f32_dpp v29, v29, v29 row_half_mirror row_mask:0xf bank_mask:0xf bound_ctrl:1
	s_and_saveexec_b64 s[20:21], s[14:15]
	ds_write_b64 v72, v[28:29] offset:51968
	s_or_b64 exec, exec, s[20:21]
	s_waitcnt lgkmcnt(1)
	v_pk_mul_f32 v[160:161], v[42:43], v[66:67] op_sel_hi:[0,1]
	v_pk_fma_f32 v[160:161], v[40:41], v[2:3], v[160:161] op_sel_hi:[0,1,1]
	v_pk_mul_f32 v[42:43], v[42:43], v[64:65] op_sel:[1,0]
	v_pk_fma_f32 v[40:41], v[40:41], v[68:69], v[42:43] op_sel:[1,0,0]
	s_waitcnt lgkmcnt(0)
	v_pk_fma_f32 v[42:43], v[36:37], v[62:63], v[160:161] op_sel_hi:[0,1,1]
	v_pk_fma_f32 v[36:37], v[36:37], v[60:61], v[40:41] op_sel:[1,0,0]
	v_pk_fma_f32 v[40:41], v[38:39], v[46:47], v[42:43] op_sel_hi:[0,1,1]
	v_pk_fma_f32 v[36:37], v[38:39], v[44:45], v[36:37] op_sel:[1,0,0]
	v_pk_add_f32 v[36:37], v[40:41], v[36:37]
	ds_read_b128 v[152:155], v1 offset:7168
	ds_read_b128 v[156:159], v1 offset:7184
	ds_read_b128 v[166:169], v1 offset:11264
	ds_read_b128 v[170:173], v1 offset:11280
	ds_read_b128 v[174:177], v1 offset:15360
	ds_read_b128 v[178:181], v1 offset:15376
	ds_read_b128 v[198:201], v1 offset:19456
	ds_read_b128 v[202:205], v1 offset:19472
	ds_read_b64 v[70:71], v73 offset:23552
	ds_read_b128 v[32:35], v74 offset:3328
	ds_read_b128 v[28:31], v74 offset:3344
	v_add_f32_dpp v36, v36, v36 quad_perm:[1,0,3,2] row_mask:0xf bank_mask:0xf bound_ctrl:1
	v_add_f32_dpp v37, v37, v37 quad_perm:[1,0,3,2] row_mask:0xf bank_mask:0xf bound_ctrl:1
	s_nop 0
	v_add_f32_dpp v36, v36, v36 quad_perm:[2,3,0,1] row_mask:0xf bank_mask:0xf bound_ctrl:1
	v_add_f32_dpp v37, v37, v37 quad_perm:[2,3,0,1] row_mask:0xf bank_mask:0xf bound_ctrl:1
	s_nop 0
	v_add_f32_dpp v36, v36, v36 row_half_mirror row_mask:0xf bank_mask:0xf bound_ctrl:1
	v_add_f32_dpp v37, v37, v37 row_half_mirror row_mask:0xf bank_mask:0xf bound_ctrl:1
	s_waitcnt lgkmcnt(8)
	v_pk_mul_f32 v[38:39], v[166:167], v[36:37] op_sel_hi:[0,1]
	s_waitcnt lgkmcnt(2)
	v_pk_fma_f32 v[38:39], v[174:175], v[70:71], v[38:39] op_sel_hi:[0,1,1] neg_lo:[0,0,1] neg_hi:[0,0,1]
	v_pk_fma_f32 v[2:3], v[2:3], v[152:153], v[38:39] op_sel_hi:[1,0,1]
	v_pk_mul_f32 v[38:39], v[166:167], v[36:37] op_sel:[1,0]
	v_pk_mul_f32 v[42:43], v[168:169], v[36:37] op_sel_hi:[0,1]
	v_pk_fma_f32 v[38:39], v[174:175], v[70:71], v[38:39] op_sel:[1,0,0] neg_lo:[0,0,1] neg_hi:[0,0,1]
	v_pk_fma_f32 v[42:43], v[176:177], v[70:71], v[42:43] op_sel_hi:[0,1,1] neg_lo:[0,0,1] neg_hi:[0,0,1]
	v_pk_fma_f32 v[68:69], v[68:69], v[152:153], v[38:39] op_sel:[0,1,0]
	v_pk_fma_f32 v[66:67], v[66:67], v[154:155], v[42:43] op_sel_hi:[1,0,1]
	v_pk_mul_f32 v[152:153], v[168:169], v[36:37] op_sel:[1,0]
	v_pk_fma_f32 v[152:153], v[176:177], v[70:71], v[152:153] op_sel:[1,0,0] neg_lo:[0,0,1] neg_hi:[0,0,1]
	v_pk_fma_f32 v[40:41], v[198:199], v[68:69], 0 op_sel:[1,0,0] op_sel_hi:[1,1,0]
	v_pk_fma_f32 v[64:65], v[64:65], v[154:155], v[152:153] op_sel:[0,1,0]
	v_pk_fma_f32 v[40:41], v[200:201], v[64:65], v[40:41] op_sel:[1,0,0]
	v_pk_mul_f32 v[42:43], v[170:171], v[36:37] op_sel_hi:[0,1]
	v_pk_fma_f32 v[42:43], v[178:179], v[70:71], v[42:43] op_sel_hi:[0,1,1] neg_lo:[0,0,1] neg_hi:[0,0,1]
	v_pk_fma_f32 v[62:63], v[62:63], v[156:157], v[42:43] op_sel_hi:[1,0,1]
	v_pk_mul_f32 v[42:43], v[170:171], v[36:37] op_sel:[1,0]
	v_pk_fma_f32 v[38:39], v[198:199], v[2:3], 0 op_sel_hi:[0,1,0]
	v_pk_fma_f32 v[42:43], v[178:179], v[70:71], v[42:43] op_sel:[1,0,0] neg_lo:[0,0,1] neg_hi:[0,0,1]
	v_pk_fma_f32 v[60:61], v[60:61], v[156:157], v[42:43] op_sel:[0,1,0]
	v_pk_mul_f32 v[42:43], v[172:173], v[36:37] op_sel_hi:[0,1]
	v_pk_fma_f32 v[38:39], v[200:201], v[66:67], v[38:39] op_sel_hi:[0,1,1]
	v_pk_fma_f32 v[42:43], v[180:181], v[70:71], v[42:43] op_sel_hi:[0,1,1] neg_lo:[0,0,1] neg_hi:[0,0,1]
	v_pk_mul_f32 v[36:37], v[172:173], v[36:37] op_sel:[1,0]
	v_pk_fma_f32 v[38:39], v[202:203], v[62:63], v[38:39] op_sel_hi:[0,1,1]
	v_pk_fma_f32 v[46:47], v[46:47], v[158:159], v[42:43] op_sel_hi:[1,0,1]
	v_pk_fma_f32 v[36:37], v[180:181], v[70:71], v[36:37] op_sel:[1,0,0] neg_lo:[0,0,1] neg_hi:[0,0,1]
	v_pk_fma_f32 v[40:41], v[202:203], v[60:61], v[40:41] op_sel:[1,0,0]
	v_pk_fma_f32 v[44:45], v[44:45], v[158:159], v[36:37] op_sel:[0,1,0]
	v_pk_fma_f32 v[36:37], v[204:205], v[46:47], v[38:39] op_sel_hi:[0,1,1]
	v_pk_fma_f32 v[38:39], v[204:205], v[44:45], v[40:41] op_sel:[1,0,0]
	v_pk_add_f32 v[36:37], v[36:37], v[38:39]
	s_nop 1
	v_add_f32_dpp v36, v36, v36 quad_perm:[1,0,3,2] row_mask:0xf bank_mask:0xf bound_ctrl:1
	v_add_f32_dpp v37, v37, v37 quad_perm:[1,0,3,2] row_mask:0xf bank_mask:0xf bound_ctrl:1
	s_nop 0
	v_add_f32_dpp v36, v36, v36 quad_perm:[2,3,0,1] row_mask:0xf bank_mask:0xf bound_ctrl:1
	v_add_f32_dpp v37, v37, v37 quad_perm:[2,3,0,1] row_mask:0xf bank_mask:0xf bound_ctrl:1
	s_nop 0
	v_add_f32_dpp v36, v36, v36 row_half_mirror row_mask:0xf bank_mask:0xf bound_ctrl:1
	v_add_f32_dpp v37, v37, v37 row_half_mirror row_mask:0xf bank_mask:0xf bound_ctrl:1
	s_and_saveexec_b64 s[20:21], s[14:15]
	ds_write_b64 v72, v[36:37] offset:52224
	s_or_b64 exec, exec, s[20:21]
	s_waitcnt lgkmcnt(1)
	v_pk_mul_f32 v[160:161], v[34:35], v[66:67] op_sel_hi:[0,1]
	v_pk_fma_f32 v[160:161], v[32:33], v[2:3], v[160:161] op_sel_hi:[0,1,1]
	v_pk_mul_f32 v[34:35], v[34:35], v[64:65] op_sel:[1,0]
	v_pk_fma_f32 v[32:33], v[32:33], v[68:69], v[34:35] op_sel:[1,0,0]
	s_waitcnt lgkmcnt(0)
	v_pk_fma_f32 v[34:35], v[28:29], v[62:63], v[160:161] op_sel_hi:[0,1,1]
	v_pk_fma_f32 v[28:29], v[28:29], v[60:61], v[32:33] op_sel:[1,0,0]
	v_pk_fma_f32 v[32:33], v[30:31], v[46:47], v[34:35] op_sel_hi:[0,1,1]
	v_pk_fma_f32 v[28:29], v[30:31], v[44:45], v[28:29] op_sel:[1,0,0]
	v_pk_add_f32 v[28:29], v[32:33], v[28:29]
	ds_read_b128 v[152:155], v1 offset:7424
	ds_read_b128 v[156:159], v1 offset:7440
	ds_read_b128 v[166:169], v1 offset:11520
	ds_read_b128 v[170:173], v1 offset:11536
	ds_read_b128 v[174:177], v1 offset:15616
	ds_read_b128 v[178:181], v1 offset:15632
	ds_read_b128 v[198:201], v1 offset:19712
	ds_read_b128 v[202:205], v1 offset:19728
	ds_read_b64 v[70:71], v73 offset:23808
	ds_read_b128 v[40:43], v74 offset:3584
	ds_read_b128 v[36:39], v74 offset:3600
	v_add_f32_dpp v28, v28, v28 quad_perm:[1,0,3,2] row_mask:0xf bank_mask:0xf bound_ctrl:1
	v_add_f32_dpp v29, v29, v29 quad_perm:[1,0,3,2] row_mask:0xf bank_mask:0xf bound_ctrl:1
	s_nop 0
	v_add_f32_dpp v28, v28, v28 quad_perm:[2,3,0,1] row_mask:0xf bank_mask:0xf bound_ctrl:1
	v_add_f32_dpp v29, v29, v29 quad_perm:[2,3,0,1] row_mask:0xf bank_mask:0xf bound_ctrl:1
	s_nop 0
	v_add_f32_dpp v28, v28, v28 row_half_mirror row_mask:0xf bank_mask:0xf bound_ctrl:1
	v_add_f32_dpp v29, v29, v29 row_half_mirror row_mask:0xf bank_mask:0xf bound_ctrl:1
	s_waitcnt lgkmcnt(8)
	v_pk_mul_f32 v[30:31], v[166:167], v[28:29] op_sel_hi:[0,1]
	s_waitcnt lgkmcnt(2)
	v_pk_fma_f32 v[30:31], v[174:175], v[70:71], v[30:31] op_sel_hi:[0,1,1] neg_lo:[0,0,1] neg_hi:[0,0,1]
	v_pk_fma_f32 v[2:3], v[2:3], v[152:153], v[30:31] op_sel_hi:[1,0,1]
	v_pk_mul_f32 v[30:31], v[166:167], v[28:29] op_sel:[1,0]
	v_pk_mul_f32 v[34:35], v[168:169], v[28:29] op_sel_hi:[0,1]
	v_pk_fma_f32 v[30:31], v[174:175], v[70:71], v[30:31] op_sel:[1,0,0] neg_lo:[0,0,1] neg_hi:[0,0,1]
	v_pk_fma_f32 v[34:35], v[176:177], v[70:71], v[34:35] op_sel_hi:[0,1,1] neg_lo:[0,0,1] neg_hi:[0,0,1]
	v_pk_fma_f32 v[68:69], v[68:69], v[152:153], v[30:31] op_sel:[0,1,0]
	v_pk_fma_f32 v[66:67], v[66:67], v[154:155], v[34:35] op_sel_hi:[1,0,1]
	v_pk_mul_f32 v[152:153], v[168:169], v[28:29] op_sel:[1,0]
	v_pk_fma_f32 v[152:153], v[176:177], v[70:71], v[152:153] op_sel:[1,0,0] neg_lo:[0,0,1] neg_hi:[0,0,1]
	v_pk_fma_f32 v[32:33], v[198:199], v[68:69], 0 op_sel:[1,0,0] op_sel_hi:[1,1,0]
	v_pk_fma_f32 v[64:65], v[64:65], v[154:155], v[152:153] op_sel:[0,1,0]
	v_pk_fma_f32 v[32:33], v[200:201], v[64:65], v[32:33] op_sel:[1,0,0]
	v_pk_mul_f32 v[34:35], v[170:171], v[28:29] op_sel_hi:[0,1]
	v_pk_fma_f32 v[34:35], v[178:179], v[70:71], v[34:35] op_sel_hi:[0,1,1] neg_lo:[0,0,1] neg_hi:[0,0,1]
	v_pk_fma_f32 v[62:63], v[62:63], v[156:157], v[34:35] op_sel_hi:[1,0,1]
	v_pk_mul_f32 v[34:35], v[170:171], v[28:29] op_sel:[1,0]
	v_pk_fma_f32 v[30:31], v[198:199], v[2:3], 0 op_sel_hi:[0,1,0]
	v_pk_fma_f32 v[34:35], v[178:179], v[70:71], v[34:35] op_sel:[1,0,0] neg_lo:[0,0,1] neg_hi:[0,0,1]
	v_pk_fma_f32 v[60:61], v[60:61], v[156:157], v[34:35] op_sel:[0,1,0]
	v_pk_mul_f32 v[34:35], v[172:173], v[28:29] op_sel_hi:[0,1]
	v_pk_fma_f32 v[30:31], v[200:201], v[66:67], v[30:31] op_sel_hi:[0,1,1]
	v_pk_fma_f32 v[34:35], v[180:181], v[70:71], v[34:35] op_sel_hi:[0,1,1] neg_lo:[0,0,1] neg_hi:[0,0,1]
	v_pk_mul_f32 v[28:29], v[172:173], v[28:29] op_sel:[1,0]
	v_pk_fma_f32 v[30:31], v[202:203], v[62:63], v[30:31] op_sel_hi:[0,1,1]
	v_pk_fma_f32 v[46:47], v[46:47], v[158:159], v[34:35] op_sel_hi:[1,0,1]
	v_pk_fma_f32 v[28:29], v[180:181], v[70:71], v[28:29] op_sel:[1,0,0] neg_lo:[0,0,1] neg_hi:[0,0,1]
	v_pk_fma_f32 v[32:33], v[202:203], v[60:61], v[32:33] op_sel:[1,0,0]
	v_pk_fma_f32 v[44:45], v[44:45], v[158:159], v[28:29] op_sel:[0,1,0]
	v_pk_fma_f32 v[28:29], v[204:205], v[46:47], v[30:31] op_sel_hi:[0,1,1]
	v_pk_fma_f32 v[30:31], v[204:205], v[44:45], v[32:33] op_sel:[1,0,0]
	v_pk_add_f32 v[28:29], v[28:29], v[30:31]
	s_nop 1
	v_add_f32_dpp v28, v28, v28 quad_perm:[1,0,3,2] row_mask:0xf bank_mask:0xf bound_ctrl:1
	v_add_f32_dpp v29, v29, v29 quad_perm:[1,0,3,2] row_mask:0xf bank_mask:0xf bound_ctrl:1
	s_nop 0
	v_add_f32_dpp v28, v28, v28 quad_perm:[2,3,0,1] row_mask:0xf bank_mask:0xf bound_ctrl:1
	v_add_f32_dpp v29, v29, v29 quad_perm:[2,3,0,1] row_mask:0xf bank_mask:0xf bound_ctrl:1
	s_nop 0
	v_add_f32_dpp v28, v28, v28 row_half_mirror row_mask:0xf bank_mask:0xf bound_ctrl:1
	v_add_f32_dpp v29, v29, v29 row_half_mirror row_mask:0xf bank_mask:0xf bound_ctrl:1
	s_and_saveexec_b64 s[20:21], s[14:15]
	ds_write_b64 v72, v[28:29] offset:52480
	s_or_b64 exec, exec, s[20:21]
	ds_read_b128 v[152:155], v1 offset:7680
	ds_read_b128 v[156:159], v1 offset:7696
	ds_read_b128 v[166:169], v1 offset:11776
	ds_read_b128 v[170:173], v1 offset:11792
	ds_read_b128 v[174:177], v1 offset:15872
	ds_read_b128 v[178:181], v1 offset:15888
	ds_read_b128 v[198:201], v1 offset:19968
	ds_read_b128 v[202:205], v1 offset:19984
	ds_read_b64 v[70:71], v73 offset:24064
	ds_read_b128 v[32:35], v74 offset:3840
	ds_read_b128 v[28:31], v74 offset:3856
	s_waitcnt lgkmcnt(12)
	v_pk_mul_f32 v[74:75], v[42:43], v[66:67] op_sel_hi:[0,1]
	v_pk_fma_f32 v[74:75], v[40:41], v[2:3], v[74:75] op_sel_hi:[0,1,1]
	v_pk_mul_f32 v[42:43], v[42:43], v[64:65] op_sel:[1,0]
	v_pk_fma_f32 v[40:41], v[40:41], v[68:69], v[42:43] op_sel:[1,0,0]
	s_waitcnt lgkmcnt(11)
	v_pk_fma_f32 v[42:43], v[36:37], v[62:63], v[74:75] op_sel_hi:[0,1,1]
	v_pk_fma_f32 v[36:37], v[36:37], v[60:61], v[40:41] op_sel:[1,0,0]
	v_pk_fma_f32 v[40:41], v[38:39], v[46:47], v[42:43] op_sel_hi:[0,1,1]
	v_pk_fma_f32 v[36:37], v[38:39], v[44:45], v[36:37] op_sel:[1,0,0]
	v_pk_add_f32 v[36:37], v[40:41], v[36:37]
	s_waitcnt lgkmcnt(10)
	s_nop 0
	v_add_f32_dpp v36, v36, v36 quad_perm:[1,0,3,2] row_mask:0xf bank_mask:0xf bound_ctrl:1
	v_add_f32_dpp v37, v37, v37 quad_perm:[1,0,3,2] row_mask:0xf bank_mask:0xf bound_ctrl:1
	s_nop 0
	v_add_f32_dpp v36, v36, v36 quad_perm:[2,3,0,1] row_mask:0xf bank_mask:0xf bound_ctrl:1
	v_add_f32_dpp v37, v37, v37 quad_perm:[2,3,0,1] row_mask:0xf bank_mask:0xf bound_ctrl:1
	s_nop 0
	v_add_f32_dpp v74, v36, v36 row_half_mirror row_mask:0xf bank_mask:0xf bound_ctrl:1
	v_add_f32_dpp v75, v37, v37 row_half_mirror row_mask:0xf bank_mask:0xf bound_ctrl:1
	s_waitcnt lgkmcnt(8)
	v_pk_mul_f32 v[36:37], v[166:167], v[74:75] op_sel_hi:[0,1]
	s_waitcnt lgkmcnt(2)
	v_pk_fma_f32 v[36:37], v[174:175], v[70:71], v[36:37] op_sel_hi:[0,1,1] neg_lo:[0,0,1] neg_hi:[0,0,1]
	v_pk_mul_f32 v[38:39], v[168:169], v[74:75] op_sel_hi:[0,1]
	v_pk_fma_f32 v[2:3], v[2:3], v[152:153], v[36:37] op_sel_hi:[1,0,1]
	v_pk_mul_f32 v[36:37], v[166:167], v[74:75] op_sel:[1,0]
	v_pk_fma_f32 v[38:39], v[176:177], v[70:71], v[38:39] op_sel_hi:[0,1,1] neg_lo:[0,0,1] neg_hi:[0,0,1]
	v_pk_fma_f32 v[36:37], v[174:175], v[70:71], v[36:37] op_sel:[1,0,0] neg_lo:[0,0,1] neg_hi:[0,0,1]
	v_pk_fma_f32 v[38:39], v[66:67], v[154:155], v[38:39] op_sel_hi:[1,0,1]
	v_pk_fma_f32 v[36:37], v[68:69], v[152:153], v[36:37] op_sel:[0,1,0]
	v_pk_mul_f32 v[66:67], v[168:169], v[74:75] op_sel:[1,0]
	v_pk_fma_f32 v[42:43], v[198:199], v[2:3], 0 op_sel_hi:[0,1,0]
	v_pk_fma_f32 v[66:67], v[176:177], v[70:71], v[66:67] op_sel:[1,0,0] neg_lo:[0,0,1] neg_hi:[0,0,1]
	v_pk_fma_f32 v[68:69], v[198:199], v[36:37], 0 op_sel:[1,0,0] op_sel_hi:[1,1,0]
	v_pk_fma_f32 v[40:41], v[64:65], v[154:155], v[66:67] op_sel:[0,1,0]
	v_pk_fma_f32 v[64:65], v[200:201], v[38:39], v[42:43] op_sel_hi:[0,1,1]
	v_pk_fma_f32 v[66:67], v[200:201], v[40:41], v[68:69] op_sel:[1,0,0]
	v_pk_mul_f32 v[42:43], v[170:171], v[74:75] op_sel_hi:[0,1]
	v_pk_fma_f32 v[42:43], v[178:179], v[70:71], v[42:43] op_sel_hi:[0,1,1] neg_lo:[0,0,1] neg_hi:[0,0,1]
	v_pk_fma_f32 v[42:43], v[62:63], v[156:157], v[42:43] op_sel_hi:[1,0,1]
	v_pk_mul_f32 v[62:63], v[170:171], v[74:75] op_sel:[1,0]
	v_pk_fma_f32 v[62:63], v[178:179], v[70:71], v[62:63] op_sel:[1,0,0] neg_lo:[0,0,1] neg_hi:[0,0,1]
	v_pk_fma_f32 v[60:61], v[60:61], v[156:157], v[62:63] op_sel:[0,1,0]
	v_pk_fma_f32 v[62:63], v[202:203], v[42:43], v[64:65] op_sel_hi:[0,1,1]
	v_pk_fma_f32 v[64:65], v[202:203], v[60:61], v[66:67] op_sel:[1,0,0]
	v_pk_mul_f32 v[66:67], v[172:173], v[74:75] op_sel_hi:[0,1]
	v_pk_fma_f32 v[66:67], v[180:181], v[70:71], v[66:67] op_sel_hi:[0,1,1] neg_lo:[0,0,1] neg_hi:[0,0,1]
	v_pk_mul_f32 v[68:69], v[172:173], v[74:75] op_sel:[1,0]
	v_pk_fma_f32 v[46:47], v[46:47], v[158:159], v[66:67] op_sel_hi:[1,0,1]
	v_pk_fma_f32 v[68:69], v[180:181], v[70:71], v[68:69] op_sel:[1,0,0] neg_lo:[0,0,1] neg_hi:[0,0,1]
	v_pk_fma_f32 v[44:45], v[44:45], v[158:159], v[68:69] op_sel:[0,1,0]
	v_pk_fma_f32 v[62:63], v[204:205], v[46:47], v[62:63] op_sel_hi:[0,1,1]
	v_pk_fma_f32 v[64:65], v[204:205], v[44:45], v[64:65] op_sel:[1,0,0]
	v_pk_add_f32 v[62:63], v[62:63], v[64:65]
	s_nop 1
	v_add_f32_dpp v62, v62, v62 quad_perm:[1,0,3,2] row_mask:0xf bank_mask:0xf bound_ctrl:1
	v_add_f32_dpp v63, v63, v63 quad_perm:[1,0,3,2] row_mask:0xf bank_mask:0xf bound_ctrl:1
	s_nop 0
	v_add_f32_dpp v62, v62, v62 quad_perm:[2,3,0,1] row_mask:0xf bank_mask:0xf bound_ctrl:1
	v_add_f32_dpp v63, v63, v63 quad_perm:[2,3,0,1] row_mask:0xf bank_mask:0xf bound_ctrl:1
	s_nop 0
	v_add_f32_dpp v62, v62, v62 row_half_mirror row_mask:0xf bank_mask:0xf bound_ctrl:1
	v_add_f32_dpp v63, v63, v63 row_half_mirror row_mask:0xf bank_mask:0xf bound_ctrl:1
	s_and_saveexec_b64 s[20:21], s[14:15]
	ds_write_b64 v72, v[62:63] offset:52736
	s_or_b64 exec, exec, s[20:21]
	s_waitcnt lgkmcnt(1)
	v_pk_mul_f32 v[66:67], v[34:35], v[38:39] op_sel_hi:[0,1]
	v_pk_mul_f32 v[68:69], v[34:35], v[40:41] op_sel:[1,0]
	v_pk_fma_f32 v[66:67], v[32:33], v[2:3], v[66:67] op_sel_hi:[0,1,1]
	v_pk_fma_f32 v[68:69], v[32:33], v[36:37], v[68:69] op_sel:[1,0,0]
	s_waitcnt lgkmcnt(0)
	v_pk_fma_f32 v[66:67], v[28:29], v[42:43], v[66:67] op_sel_hi:[0,1,1]
	v_pk_fma_f32 v[68:69], v[28:29], v[60:61], v[68:69] op_sel:[1,0,0]
	v_pk_fma_f32 v[66:67], v[30:31], v[46:47], v[66:67] op_sel_hi:[0,1,1]
	v_pk_fma_f32 v[68:69], v[30:31], v[44:45], v[68:69] op_sel:[1,0,0]
	v_pk_add_f32 v[66:67], v[66:67], v[68:69]
	ds_read_b64 v[74:75], v73 offset:24320
	ds_read_b128 v[152:155], v1 offset:20240
	ds_read_b128 v[156:159], v1 offset:20224
	ds_read_b128 v[166:169], v1 offset:16144
	ds_read_b128 v[62:65], v1 offset:16128
	ds_read_b128 v[170:173], v1 offset:12048
	ds_read_b128 v[174:177], v1 offset:12032
	ds_read_b128 v[178:181], v1 offset:7936
	ds_read_b128 v[198:201], v1 offset:7952
	v_add_f32_dpp v66, v66, v66 quad_perm:[1,0,3,2] row_mask:0xf bank_mask:0xf bound_ctrl:1
	v_add_f32_dpp v67, v67, v67 quad_perm:[1,0,3,2] row_mask:0xf bank_mask:0xf bound_ctrl:1
	s_nop 0
	v_add_f32_dpp v66, v66, v66 quad_perm:[2,3,0,1] row_mask:0xf bank_mask:0xf bound_ctrl:1
	v_add_f32_dpp v67, v67, v67 quad_perm:[2,3,0,1] row_mask:0xf bank_mask:0xf bound_ctrl:1
	s_nop 0
	v_add_f32_dpp v160, v66, v66 row_half_mirror row_mask:0xf bank_mask:0xf bound_ctrl:1
	v_add_f32_dpp v161, v67, v67 row_half_mirror row_mask:0xf bank_mask:0xf bound_ctrl:1
	s_waitcnt lgkmcnt(2)
	v_pk_mul_f32 v[66:67], v[174:175], v[160:161] op_sel_hi:[0,1]
	v_pk_fma_f32 v[66:67], v[74:75], v[62:63], v[66:67] op_sel_hi:[1,0,1] neg_lo:[0,0,1] neg_hi:[0,0,1]
	s_waitcnt lgkmcnt(1)
	v_pk_fma_f32 v[70:71], v[2:3], v[178:179], v[66:67] op_sel_hi:[1,0,1]
	v_pk_mul_f32 v[2:3], v[174:175], v[160:161] op_sel:[1,0]
	s_nop 0
	v_pk_fma_f32 v[2:3], v[74:75], v[62:63], v[2:3] op_sel:[0,1,0] neg_lo:[0,0,1] neg_hi:[0,0,1]
	v_pk_mul_f32 v[62:63], v[176:177], v[160:161] op_sel_hi:[0,1]
	v_pk_fma_f32 v[62:63], v[74:75], v[64:65], v[62:63] op_sel_hi:[1,0,1] neg_lo:[0,0,1] neg_hi:[0,0,1]
	v_pk_fma_f32 v[66:67], v[38:39], v[180:181], v[62:63] op_sel_hi:[1,0,1]
	v_pk_mul_f32 v[62:63], v[176:177], v[160:161] op_sel:[1,0]
	v_pk_fma_f32 v[68:69], v[36:37], v[178:179], v[2:3] op_sel:[0,1,0]
	v_pk_fma_f32 v[62:63], v[74:75], v[64:65], v[62:63] op_sel:[0,1,0] neg_lo:[0,0,1] neg_hi:[0,0,1]
	v_pk_fma_f32 v[36:37], v[156:157], v[68:69], 0 op_sel:[1,0,0] op_sel_hi:[1,1,0]
	v_pk_fma_f32 v[64:65], v[40:41], v[180:181], v[62:63] op_sel:[0,1,0]
	v_pk_fma_f32 v[36:37], v[158:159], v[64:65], v[36:37] op_sel:[1,0,0]
	v_pk_mul_f32 v[38:39], v[170:171], v[160:161] op_sel_hi:[0,1]
	v_pk_fma_f32 v[38:39], v[74:75], v[166:167], v[38:39] op_sel_hi:[1,0,1] neg_lo:[0,0,1] neg_hi:[0,0,1]
	s_waitcnt lgkmcnt(0)
	v_pk_fma_f32 v[62:63], v[42:43], v[198:199], v[38:39] op_sel_hi:[1,0,1]
	v_pk_mul_f32 v[38:39], v[170:171], v[160:161] op_sel:[1,0]
	v_pk_fma_f32 v[2:3], v[156:157], v[70:71], 0 op_sel_hi:[0,1,0]
	v_pk_fma_f32 v[38:39], v[74:75], v[166:167], v[38:39] op_sel:[0,1,0] neg_lo:[0,0,1] neg_hi:[0,0,1]
	v_mov_b32_e32 v42, v169
	v_pk_fma_f32 v[60:61], v[60:61], v[198:199], v[38:39] op_sel:[0,1,0]
	v_pk_mul_f32 v[38:39], v[172:173], v[160:161] op_sel_hi:[0,1]
	v_pk_fma_f32 v[38:39], v[74:75], v[168:169], v[38:39] op_sel_hi:[1,0,1] neg_lo:[0,0,1] neg_hi:[0,0,1]
	v_pk_mul_f32 v[40:41], v[172:173], v[160:161] op_sel:[1,0]
	v_pk_fma_f32 v[2:3], v[158:159], v[66:67], v[2:3] op_sel_hi:[0,1,1]
	v_pk_fma_f32 v[46:47], v[46:47], v[200:201], v[38:39] op_sel_hi:[1,0,1]
	v_pk_fma_f32 v[40:41], v[74:75], v[42:43], v[40:41] op_sel_hi:[1,0,1] neg_lo:[0,0,1] neg_hi:[0,0,1]
	v_pk_fma_f32 v[2:3], v[152:153], v[62:63], v[2:3] op_sel_hi:[0,1,1]
	v_pk_fma_f32 v[36:37], v[152:153], v[60:61], v[36:37] op_sel:[1,0,0]
	v_pk_fma_f32 v[44:45], v[44:45], v[200:201], v[40:41] op_sel:[0,1,0]
	v_mov_b32_e32 v38, v155
	v_pk_fma_f32 v[2:3], v[154:155], v[46:47], v[2:3] op_sel_hi:[0,1,1]
	v_pk_fma_f32 v[36:37], v[38:39], v[44:45], v[36:37] op_sel_hi:[0,1,1]
	v_pk_add_f32 v[2:3], v[2:3], v[36:37]
	s_nop 1
	v_add_f32_dpp v2, v2, v2 quad_perm:[1,0,3,2] row_mask:0xf bank_mask:0xf bound_ctrl:1
	v_add_f32_dpp v3, v3, v3 quad_perm:[1,0,3,2] row_mask:0xf bank_mask:0xf bound_ctrl:1
	s_nop 0
	v_add_f32_dpp v2, v2, v2 quad_perm:[2,3,0,1] row_mask:0xf bank_mask:0xf bound_ctrl:1
	v_add_f32_dpp v3, v3, v3 quad_perm:[2,3,0,1] row_mask:0xf bank_mask:0xf bound_ctrl:1
	s_nop 0
	v_mov_b32_dpp v36, v2 row_half_mirror row_mask:0xf bank_mask:0xf bound_ctrl:1
	v_mov_b32_dpp v37, v3 row_half_mirror row_mask:0xf bank_mask:0xf bound_ctrl:1
	s_and_saveexec_b64 s[20:21], s[14:15]
	s_cbranch_execz .LBB0_575
	v_pk_add_f32 v[2:3], v[2:3], v[36:37]
	ds_write_b64 v72, v[2:3] offset:52992
	s_branch .LBB0_575

.Lm4_ok:
	v_mov_b64_e32 v[162:163], 0x200
	s_and_b32 s14, s41, 0x7fffff8
	s_add_i32 s14, s14, s18
	v_lshl_or_b32 v50, s14, 5, v1
	v_readlane_b32 s52, v253, 32
	v_ashrrev_i32_e32 v51, 31, v50
	v_readlane_b32 s53, v253, 33
	s_lshl_b32 s14, s39, 5
	s_and_b32 s14, s14, 0xffffff00
	v_lshl_add_u64 v[50:51], v[50:51], 2, s[52:53]
	global_load_dword v88, v[50:51], off
	global_load_dword v89, v[50:51], off offset:64
	global_load_dword v90, v[50:51], off offset:512
	global_load_dword v91, v[50:51], off offset:576
	v_add_u32_e32 v50, s14, v135
	s_lshl_b32 s14, s39, 7
	s_and_b32 s17, s14, 0x380
	s_lshl_b32 s14, s17, 1
	s_add_u32 s14, s22, s14
	v_ashrrev_i32_e32 v51, 31, v50
	s_addc_u32 s15, s23, 0
	v_lshlrev_b64 v[80:81], 11, v[50:51]
	v_lshl_add_u64 v[52:53], s[14:15], 0, v[80:81]
	v_mov_b32_e32 v139, v0
	v_lshl_add_u64 v[52:53], v[52:53], 0, v[138:139]
	global_load_dwordx4 v[92:95], v[52:53], off sc1
	global_load_dwordx4 v[74:77], v[52:53], off offset:64 sc1
	v_or_b32_e32 v52, 16, v50
	v_ashrrev_i32_e32 v53, 31, v52
	v_lshlrev_b64 v[84:85], 11, v[52:53]
	v_lshl_add_u64 v[52:53], s[14:15], 0, v[84:85]
	v_lshl_add_u64 v[52:53], v[52:53], 0, v[138:139]
	global_load_dwordx4 v[70:73], v[52:53], off sc1
	global_load_dwordx4 v[66:69], v[52:53], off offset:64 sc1
	v_add_u32_e32 v52, 0x80, v50
	v_ashrrev_i32_e32 v53, 31, v52
	v_lshlrev_b64 v[82:83], 11, v[52:53]
	v_lshl_add_u64 v[52:53], s[14:15], 0, v[82:83]
	v_lshl_add_u64 v[52:53], v[52:53], 0, v[138:139]
	global_load_dwordx4 v[62:65], v[52:53], off sc1
	global_load_dwordx4 v[58:61], v[52:53], off offset:64 sc1
	v_add_u32_e32 v50, 0x90, v50
	v_ashrrev_i32_e32 v51, 31, v50
	v_lshlrev_b64 v[78:79], 11, v[50:51]
	v_lshl_add_u64 v[50:51], s[14:15], 0, v[78:79]
	v_lshl_add_u64 v[50:51], v[50:51], 0, v[138:139]
	global_load_dwordx4 v[54:57], v[50:51], off sc1
	s_nop 0
	global_load_dwordx4 v[50:53], v[50:51], off offset:64 sc1
	v_readlane_b32 s60, v253, 40
	v_readlane_b32 s61, v253, 41
	v_or_b32_e32 v96, s17, v140
	v_and_b32_e32 v97, 0xffff0000, v236
	v_lshl_add_u64 v[86:87], s[60:61], 0, v[80:81]
	v_lshlrev_b32_e32 v80, 1, v96
	v_lshlrev_b32_e32 v96, 16, v236
	v_mov_b32_e32 v81, v0
	v_lshl_add_u64 v[86:87], v[86:87], 0, v[80:81]
	s_mov_b64 s[14:15], -1
	v_mov_b32_e32 v236, 0
	v_readlane_b32 s54, v253, 34
	v_readlane_b32 s55, v253, 35
	v_readlane_b32 s56, v253, 36
	v_readlane_b32 s57, v253, 37
	v_readlane_b32 s58, v253, 38
	v_readlane_b32 s59, v253, 39
	v_readlane_b32 s62, v253, 42
	v_readlane_b32 s63, v253, 43
	v_readlane_b32 s64, v253, 44
	v_readlane_b32 s65, v253, 45
	v_readlane_b32 s66, v253, 46
	v_readlane_b32 s67, v253, 47
	s_waitcnt vmcnt(0)
	v_lshlrev_b32_e32 v98, 16, v92
	v_and_b32_e32 v99, 0xffff0000, v92
	v_pk_add_f32 v[96:97], v[96:97], v[98:99]
	v_lshlrev_b32_e32 v98, 16, v93
	v_cvt_pk_bf16_f32 v92, v96, v97
	v_lshlrev_b32_e32 v96, 16, v235
	v_and_b32_e32 v97, 0xffff0000, v235
	v_and_b32_e32 v99, 0xffff0000, v93
	v_pk_add_f32 v[96:97], v[96:97], v[98:99]
	v_lshlrev_b32_e32 v98, 16, v94
	v_cvt_pk_bf16_f32 v93, v96, v97
	v_lshlrev_b32_e32 v96, 16, v234
	v_and_b32_e32 v97, 0xffff0000, v234
	v_and_b32_e32 v99, 0xffff0000, v94
	v_pk_add_f32 v[96:97], v[96:97], v[98:99]
	v_lshlrev_b32_e32 v98, 16, v95
	v_cvt_pk_bf16_f32 v94, v96, v97
	v_lshlrev_b32_e32 v96, 16, v233
	v_and_b32_e32 v97, 0xffff0000, v233
	v_and_b32_e32 v99, 0xffff0000, v95
	v_pk_add_f32 v[96:97], v[96:97], v[98:99]
	v_mov_b32_e32 v235, 0
	v_cvt_pk_bf16_f32 v95, v96, v97
	global_store_dwordx4 v[86:87], v[92:95], off
	v_mov_b32_e32 v233, 0
	v_mov_b32_e32 v234, 0
	v_lshlrev_b32_e32 v92, 16, v232
	v_and_b32_e32 v93, 0xffff0000, v232
	v_lshlrev_b32_e32 v94, 16, v74
	v_and_b32_e32 v95, 0xffff0000, v74
	v_pk_add_f32 v[92:93], v[92:93], v[94:95]
	v_lshlrev_b32_e32 v94, 16, v75
	v_cvt_pk_bf16_f32 v74, v92, v93
	v_lshlrev_b32_e32 v92, 16, v231
	v_and_b32_e32 v93, 0xffff0000, v231
	v_and_b32_e32 v95, 0xffff0000, v75
	v_pk_add_f32 v[92:93], v[92:93], v[94:95]
	v_lshlrev_b32_e32 v94, 16, v76
	v_cvt_pk_bf16_f32 v75, v92, v93
	v_lshlrev_b32_e32 v92, 16, v230
	v_and_b32_e32 v93, 0xffff0000, v230
	v_and_b32_e32 v95, 0xffff0000, v76
	v_pk_add_f32 v[92:93], v[92:93], v[94:95]
	v_lshlrev_b32_e32 v94, 16, v77
	v_cvt_pk_bf16_f32 v76, v92, v93
	v_lshlrev_b32_e32 v92, 16, v229
	v_and_b32_e32 v93, 0xffff0000, v229
	v_and_b32_e32 v95, 0xffff0000, v77
	v_pk_add_f32 v[92:93], v[92:93], v[94:95]
	v_mov_b32_e32 v231, 0
	v_cvt_pk_bf16_f32 v77, v92, v93
	global_store_dwordx4 v[86:87], v[74:77], off offset:64
	v_mov_b32_e32 v232, 0
	v_mov_b32_e32 v229, 0
	v_lshl_add_u64 v[74:75], s[60:61], 0, v[84:85]
	v_lshlrev_b32_e32 v76, 16, v228
	v_and_b32_e32 v77, 0xffff0000, v228
	v_lshlrev_b32_e32 v84, 16, v70
	v_and_b32_e32 v85, 0xffff0000, v70
	v_pk_add_f32 v[76:77], v[76:77], v[84:85]
	v_lshlrev_b32_e32 v84, 16, v71
	v_cvt_pk_bf16_f32 v70, v76, v77
	v_lshlrev_b32_e32 v76, 16, v227
	v_and_b32_e32 v77, 0xffff0000, v227
	v_and_b32_e32 v85, 0xffff0000, v71
	v_pk_add_f32 v[76:77], v[76:77], v[84:85]
	v_lshlrev_b32_e32 v84, 16, v72
	v_cvt_pk_bf16_f32 v71, v76, v77
	v_lshlrev_b32_e32 v76, 16, v226
	v_and_b32_e32 v77, 0xffff0000, v226
	v_and_b32_e32 v85, 0xffff0000, v72
	v_pk_add_f32 v[76:77], v[76:77], v[84:85]
	v_lshlrev_b32_e32 v84, 16, v73
	v_cvt_pk_bf16_f32 v72, v76, v77
	v_lshlrev_b32_e32 v76, 16, v225
	v_and_b32_e32 v77, 0xffff0000, v225
	v_and_b32_e32 v85, 0xffff0000, v73
	v_pk_add_f32 v[76:77], v[76:77], v[84:85]
	v_lshl_add_u64 v[74:75], v[74:75], 0, v[80:81]
	v_cvt_pk_bf16_f32 v73, v76, v77
	global_store_dwordx4 v[74:75], v[70:73], off
	v_mov_b32_e32 v230, 0
	v_mov_b32_e32 v227, 0
	v_lshlrev_b32_e32 v70, 16, v224
	v_and_b32_e32 v71, 0xffff0000, v224
	v_lshlrev_b32_e32 v72, 16, v66
	v_and_b32_e32 v73, 0xffff0000, v66
	v_pk_add_f32 v[70:71], v[70:71], v[72:73]
	v_lshlrev_b32_e32 v72, 16, v67
	v_cvt_pk_bf16_f32 v66, v70, v71
	v_lshlrev_b32_e32 v70, 16, v223
	v_and_b32_e32 v71, 0xffff0000, v223
	v_and_b32_e32 v73, 0xffff0000, v67
	v_pk_add_f32 v[70:71], v[70:71], v[72:73]
	v_lshlrev_b32_e32 v72, 16, v68
	v_cvt_pk_bf16_f32 v67, v70, v71
	v_lshlrev_b32_e32 v70, 16, v222
	v_and_b32_e32 v71, 0xffff0000, v222
	v_and_b32_e32 v73, 0xffff0000, v68
	v_pk_add_f32 v[70:71], v[70:71], v[72:73]
	v_lshlrev_b32_e32 v72, 16, v69
	v_cvt_pk_bf16_f32 v68, v70, v71
	v_lshlrev_b32_e32 v70, 16, v221
	v_and_b32_e32 v71, 0xffff0000, v221
	v_and_b32_e32 v73, 0xffff0000, v69
	v_pk_add_f32 v[70:71], v[70:71], v[72:73]
	v_mov_b32_e32 v228, 0
	v_cvt_pk_bf16_f32 v69, v70, v71
	global_store_dwordx4 v[74:75], v[66:69], off offset:64
	v_lshlrev_b32_e32 v70, 16, v62
	v_and_b32_e32 v71, 0xffff0000, v62
	v_lshlrev_b32_e32 v68, 16, v220
	v_and_b32_e32 v69, 0xffff0000, v220
	v_pk_add_f32 v[68:69], v[68:69], v[70:71]
	v_lshlrev_b32_e32 v70, 16, v63
	v_cvt_pk_bf16_f32 v62, v68, v69
	v_lshlrev_b32_e32 v68, 16, v219
	v_and_b32_e32 v69, 0xffff0000, v219
	v_and_b32_e32 v71, 0xffff0000, v63
	v_pk_add_f32 v[68:69], v[68:69], v[70:71]
	v_lshlrev_b32_e32 v70, 16, v64
	v_cvt_pk_bf16_f32 v63, v68, v69
	v_lshlrev_b32_e32 v68, 16, v218
	v_and_b32_e32 v69, 0xffff0000, v218
	v_and_b32_e32 v71, 0xffff0000, v64
	v_pk_add_f32 v[68:69], v[68:69], v[70:71]
	v_lshlrev_b32_e32 v70, 16, v65
	v_cvt_pk_bf16_f32 v64, v68, v69
	v_lshlrev_b32_e32 v68, 16, v217
	v_and_b32_e32 v69, 0xffff0000, v217
	v_and_b32_e32 v71, 0xffff0000, v65
	v_lshl_add_u64 v[66:67], s[60:61], 0, v[82:83]
	v_pk_add_f32 v[68:69], v[68:69], v[70:71]
	v_lshl_add_u64 v[66:67], v[66:67], 0, v[80:81]
	v_cvt_pk_bf16_f32 v65, v68, v69
	global_store_dwordx4 v[66:67], v[62:65], off
	v_mov_b32_e32 v225, 0
	v_mov_b32_e32 v226, 0
	v_lshlrev_b32_e32 v62, 16, v216
	v_and_b32_e32 v63, 0xffff0000, v216
	v_lshlrev_b32_e32 v64, 16, v58
	v_and_b32_e32 v65, 0xffff0000, v58
	v_pk_add_f32 v[62:63], v[62:63], v[64:65]
	v_lshlrev_b32_e32 v64, 16, v59
	v_cvt_pk_bf16_f32 v58, v62, v63
	v_lshlrev_b32_e32 v62, 16, v215
	v_and_b32_e32 v63, 0xffff0000, v215
	v_and_b32_e32 v65, 0xffff0000, v59
	v_pk_add_f32 v[62:63], v[62:63], v[64:65]
	v_lshlrev_b32_e32 v64, 16, v60
	v_cvt_pk_bf16_f32 v59, v62, v63
	v_lshlrev_b32_e32 v62, 16, v214
	v_and_b32_e32 v63, 0xffff0000, v214
	v_and_b32_e32 v65, 0xffff0000, v60
	v_pk_add_f32 v[62:63], v[62:63], v[64:65]
	v_lshlrev_b32_e32 v64, 16, v61
	v_cvt_pk_bf16_f32 v60, v62, v63
	v_lshlrev_b32_e32 v62, 16, v213
	v_and_b32_e32 v63, 0xffff0000, v213
	v_and_b32_e32 v65, 0xffff0000, v61
	v_pk_add_f32 v[62:63], v[62:63], v[64:65]
	v_mov_b32_e32 v223, 0
	v_cvt_pk_bf16_f32 v61, v62, v63
	global_store_dwordx4 v[66:67], v[58:61], off offset:64
	v_lshlrev_b32_e32 v62, 16, v54
	v_and_b32_e32 v63, 0xffff0000, v54
	v_lshlrev_b32_e32 v60, 16, v212
	v_and_b32_e32 v61, 0xffff0000, v212
	v_pk_add_f32 v[60:61], v[60:61], v[62:63]
	v_lshlrev_b32_e32 v62, 16, v55
	v_cvt_pk_bf16_f32 v54, v60, v61
	v_lshlrev_b32_e32 v60, 16, v211
	v_and_b32_e32 v61, 0xffff0000, v211
	v_and_b32_e32 v63, 0xffff0000, v55
	v_pk_add_f32 v[60:61], v[60:61], v[62:63]
	v_lshlrev_b32_e32 v62, 16, v56
	v_cvt_pk_bf16_f32 v55, v60, v61
	v_lshlrev_b32_e32 v60, 16, v210
	v_and_b32_e32 v61, 0xffff0000, v210
	v_and_b32_e32 v63, 0xffff0000, v56
	v_pk_add_f32 v[60:61], v[60:61], v[62:63]
	v_lshlrev_b32_e32 v62, 16, v57
	v_cvt_pk_bf16_f32 v56, v60, v61
	v_lshlrev_b32_e32 v60, 16, v209
	v_and_b32_e32 v61, 0xffff0000, v209
	v_and_b32_e32 v63, 0xffff0000, v57
	v_lshl_add_u64 v[58:59], s[60:61], 0, v[78:79]
	v_pk_add_f32 v[60:61], v[60:61], v[62:63]
	v_lshl_add_u64 v[58:59], v[58:59], 0, v[80:81]
	v_cvt_pk_bf16_f32 v57, v60, v61
	global_store_dwordx4 v[58:59], v[54:57], off
	v_mov_b32_e32 v224, 0
	v_mov_b32_e32 v221, 0
	v_lshlrev_b32_e32 v54, 16, v208
	v_and_b32_e32 v55, 0xffff0000, v208
	v_lshlrev_b32_e32 v56, 16, v50
	v_and_b32_e32 v57, 0xffff0000, v50
	v_pk_add_f32 v[54:55], v[54:55], v[56:57]
	v_lshlrev_b32_e32 v56, 16, v51
	v_cvt_pk_bf16_f32 v50, v54, v55
	v_lshlrev_b32_e32 v54, 16, v207
	v_and_b32_e32 v55, 0xffff0000, v207
	v_and_b32_e32 v57, 0xffff0000, v51
	v_pk_add_f32 v[54:55], v[54:55], v[56:57]
	v_lshlrev_b32_e32 v56, 16, v52
	v_cvt_pk_bf16_f32 v51, v54, v55
	v_lshlrev_b32_e32 v54, 16, v206
	v_and_b32_e32 v55, 0xffff0000, v206
	v_and_b32_e32 v57, 0xffff0000, v52
	v_pk_add_f32 v[54:55], v[54:55], v[56:57]
	v_lshlrev_b32_e32 v56, 16, v53
	v_cvt_pk_bf16_f32 v52, v54, v55
	v_lshlrev_b32_e32 v54, 16, v205
	v_and_b32_e32 v55, 0xffff0000, v205
	v_and_b32_e32 v57, 0xffff0000, v53
	v_pk_add_f32 v[54:55], v[54:55], v[56:57]
	v_mov_b32_e32 v222, 0
	v_cvt_pk_bf16_f32 v53, v54, v55
	v_mov_b32_e32 v219, 0
	v_mov_b32_e32 v220, 0
	v_mov_b32_e32 v217, 0
	v_mov_b32_e32 v218, 0
	v_mov_b32_e32 v215, 0
	v_mov_b32_e32 v216, 0
	v_mov_b32_e32 v213, 0
	v_mov_b32_e32 v214, 0
	v_mov_b32_e32 v211, 0
	v_mov_b32_e32 v212, 0
	v_mov_b32_e32 v209, 0
	v_mov_b32_e32 v210, 0
	v_mov_b32_e32 v207, 0
	v_mov_b32_e32 v208, 0
	v_mov_b32_e32 v205, 0
	v_mov_b32_e32 v206, 0
	global_store_dwordx4 v[58:59], v[50:53], off offset:64
	ds_write2_b32 v137, v88, v89 offset1:16
	ds_write2_b32 v137, v90, v91 offset0:128 offset1:144
	s_branch .LBB0_1206
